# v4 plus GEMM1 ALIGN_EPI barrier of the leading half moved a few hundred instructions into its epilogue (its VALU runs under the lagging half's last MFMA segment)
# speedup vs baseline: 1.0123x; 1.0004x over previous
; #define PG8_STAGE(bufoff, gbase, voff) do { _Pragma("unroll") for (int _i = 0; _i < 2; ++_i) \
;         __builtin_amdgcn_global_load_lds((const unsigned*)((const char*)(gbase) + (voff)[_i]), (LAS unsigned*)(lds + (bufoff) + ldsw + _i * 8192), 16, 0, 0); } while (0)
; #define PG8_LDA(dst, b, h) do { _Pragma("unroll") for (int m = 0; m < 4; ++m) _Pragma("unroll") for (int k = 0; k < 2; ++k) dst[m][k] = *(const LAS bf16x8*)(lds + PG8_SA(b, h) + aoff + m * 2048 + k * 1024); } while (0)
; #define PG8_LDB(dst, b, h) do { _Pragma("unroll") for (int n = 0; n < 2; ++n) _Pragma("unroll") for (int k = 0; k < 2; ++k) dst[n][k] = *(const LAS bf16x8*)(lds + PG8_SB(b, h) + boff + n * 2048 + k * 1024); } while (0)
; #define PG8_WAIT_V(n) asm volatile("s_waitcnt vmcnt(" #n ")" ::: "memory")
; #define PG8_BAR __builtin_amdgcn_s_barrier()
; template <class Epi>
; __device__ __forceinline__ void gemm_phase(LAS unsigned char* lds, const Gemm g, const StaticOrder& S, const Epi& E) {
;     ...
;         for (int t = hf * nth; t < (hf + 1) * nth; t += 2) {
;             const bool last = (t == nt - 2);
;             const char* a1 = cA + (size_t)(t + 1) * kstep;
;             const char* a2 = last ? nA : cA + (size_t)(t + 2) * kstep; const char* b2 = last ? nB : cB + (size_t)(t + 2) * kstep;
;             const char* a3 = a2 + kstep; const char* b3 = b2 + kstep;
;             PG8_LDB(B0, 0, 0); PG8_LDB(B1, 0, 1); PG8_SCHED; PG8_LDA(At, 0, 0); PG8_STAGE(PG8_SA(1, 1), a1 + hstepA, voffA);
;             PG8_WAIT_V(8); PG8_WAIT_L(0); PG8_BAR; PG8_MMA(0, 0, At, B0); PG8_MMA(0, 1, At, B1); PG8_BAR; PG8_SCHED;
;             PG8_LDA(At, 0, 1); PG8_STAGE(PG8_SB(0, 0), b2, voffB); PG8_STAGE(PG8_SB(0, 1), b2 + hstepB, voffB); PG8_STAGE(PG8_SA(0, 0), a2, voffA);
;             PG8_WAIT_V(8); PG8_WAIT_L(0); PG8_BAR; PG8_MMA(1, 0, At, B0); PG8_MMA(1, 1, At, B1); PG8_BAR; PG8_SCHED;
;             PG8_LDB(B0, 1, 0); PG8_LDB(B1, 1, 1); PG8_SCHED; PG8_LDA(At, 1, 0); PG8_STAGE(PG8_SA(0, 1), a2 + hstepA, voffA);
;             PG8_WAIT_V(8); PG8_WAIT_L(0); PG8_BAR; PG8_MMA(0, 0, At, B0); PG8_MMA(0, 1, At, B1); PG8_BAR; PG8_SCHED;
;             PG8_LDA(At, 1, 1); PG8_STAGE(PG8_SB(1, 0), b3, voffB); PG8_STAGE(PG8_SB(1, 1), b3 + hstepB, voffB); PG8_STAGE(PG8_SA(1, 0), a3, voffA);
;             PG8_WAIT_V(8); PG8_WAIT_L(0); PG8_BAR; PG8_MMA(1, 0, At, B0); PG8_MMA(1, 1, At, B1); PG8_BAR; PG8_SCHED;
.LBB0_160:
	ds_read_b128 v[146:149], v164
	ds_read_b128 v[150:153], v164 offset:1024
	ds_read_b128 v[154:157], v164 offset:2048
	ds_read_b128 v[158:161], v164 offset:3072
	ds_read_b128 v[168:171], v165
	ds_read_b128 v[172:175], v165 offset:1024
	ds_read_b128 v[176:179], v165 offset:2048
	ds_read_b128 v[180:183], v165 offset:3072
	s_add_u32 s42, s8, 0xfffc0080
	s_addc_u32 s43, s9, -1
	s_cmp_eq_u32 s88, 12
	s_cselect_b32 s43, s7, s43
	s_cselect_b32 s42, s12, s42
	s_cselect_b32 s87, s16, s79
	s_cselect_b32 s86, s17, s77
	v_lshl_add_u64 v[192:193], s[8:9], 0, v[138:139]
	s_add_i32 m0, s27, 0xc000
	ds_read_b128 v[184:187], v166
	ds_read_b128 v[188:191], v166 offset:1024
	ds_read_b128 v[196:199], v166 offset:2048
	ds_read_b128 v[200:203], v166 offset:3072
	ds_read_b128 v[204:207], v166 offset:4096
	ds_read_b128 v[208:211], v166 offset:5120
	ds_read_b128 v[212:215], v166 offset:6144
	ds_read_b128 v[216:219], v166 offset:7168
	global_load_lds_dwordx4 v[192:193], off
	v_lshl_add_u64 v[192:193], s[8:9], 0, v[140:141]
	s_add_i32 m0, s27, 0xe000
	s_nop 0
	global_load_lds_dwordx4 v[192:193], off
	s_waitcnt vmcnt(8)
	s_waitcnt lgkmcnt(0)
	s_barrier
	s_setprio 1
	s_waitcnt lgkmcnt(0)
	v_mfma_f32_16x16x32_bf16 v[124:127], v[146:149], v[184:187], v[124:127]
	v_mfma_f32_16x16x32_bf16 v[116:119], v[154:157], v[184:187], v[116:119]
	v_mfma_f32_16x16x32_bf16 v[108:111], v[146:149], v[196:199], v[108:111]
	v_mfma_f32_16x16x32_bf16 v[100:103], v[154:157], v[196:199], v[100:103]
	v_mfma_f32_16x16x32_bf16 v[92:95], v[146:149], v[204:207], v[92:95]
	v_mfma_f32_16x16x32_bf16 v[84:87], v[154:157], v[204:207], v[84:87]
	v_mfma_f32_16x16x32_bf16 v[76:79], v[146:149], v[212:215], v[76:79]
	v_mfma_f32_16x16x32_bf16 v[68:71], v[154:157], v[212:215], v[68:71]
	v_mfma_f32_16x16x32_bf16 v[124:127], v[150:153], v[188:191], v[124:127]
	v_mfma_f32_16x16x32_bf16 v[116:119], v[158:161], v[188:191], v[116:119]
	v_mfma_f32_16x16x32_bf16 v[108:111], v[150:153], v[200:203], v[108:111]
	v_mfma_f32_16x16x32_bf16 v[100:103], v[158:161], v[200:203], v[100:103]
	v_mfma_f32_16x16x32_bf16 v[92:95], v[150:153], v[208:211], v[92:95]
	v_mfma_f32_16x16x32_bf16 v[84:87], v[158:161], v[208:211], v[84:87]
	v_mfma_f32_16x16x32_bf16 v[76:79], v[150:153], v[216:219], v[76:79]
	v_mfma_f32_16x16x32_bf16 v[68:71], v[158:161], v[216:219], v[68:71]
	s_setprio 0
	s_setprio 1
	v_mfma_f32_16x16x32_bf16 v[120:123], v[168:171], v[184:187], v[120:123]
	v_mfma_f32_16x16x32_bf16 v[112:115], v[176:179], v[184:187], v[112:115]
	v_mfma_f32_16x16x32_bf16 v[104:107], v[168:171], v[196:199], v[104:107]
	v_mfma_f32_16x16x32_bf16 v[96:99], v[176:179], v[196:199], v[96:99]
	v_mfma_f32_16x16x32_bf16 v[88:91], v[168:171], v[204:207], v[88:91]
	v_mfma_f32_16x16x32_bf16 v[80:83], v[176:179], v[204:207], v[80:83]
	v_mfma_f32_16x16x32_bf16 v[72:75], v[168:171], v[212:215], v[72:75]
	v_mfma_f32_16x16x32_bf16 v[64:67], v[176:179], v[212:215], v[64:67]
	v_mfma_f32_16x16x32_bf16 v[120:123], v[172:175], v[188:191], v[120:123]
	v_mfma_f32_16x16x32_bf16 v[112:115], v[180:183], v[188:191], v[112:115]
	v_mfma_f32_16x16x32_bf16 v[104:107], v[172:175], v[200:203], v[104:107]
	v_mfma_f32_16x16x32_bf16 v[96:99], v[180:183], v[200:203], v[96:99]
	v_mfma_f32_16x16x32_bf16 v[88:91], v[172:175], v[208:211], v[88:91]
	v_mfma_f32_16x16x32_bf16 v[80:83], v[180:183], v[208:211], v[80:83]
	v_mfma_f32_16x16x32_bf16 v[72:75], v[172:175], v[216:219], v[72:75]
	v_mfma_f32_16x16x32_bf16 v[64:67], v[180:183], v[216:219], v[64:67]
	s_setprio 0
	s_barrier
	s_add_i32 s89, s1, s3
	v_lshl_add_u64 v[192:193], s[86:87], 0, v[130:131]
	s_mov_b32 m0, s89
	ds_read_b128 v[184:187], v166 offset:16384
	ds_read_b128 v[188:191], v166 offset:17408
	ds_read_b128 v[196:199], v166 offset:18432
	ds_read_b128 v[200:203], v166 offset:19456
	ds_read_b128 v[204:207], v166 offset:20480
	ds_read_b128 v[208:211], v166 offset:21504
	ds_read_b128 v[212:215], v166 offset:22528
	ds_read_b128 v[216:219], v166 offset:23552
	global_load_lds_dwordx4 v[192:193], off
	s_add_i32 m0, s89, 0x2000
	s_add_u32 s90, s86, 0x40000
	v_lshl_add_u64 v[220:221], s[86:87], 0, v[134:135]
	s_addc_u32 s91, s87, 0
	s_add_i32 s89, s20, s3
	global_load_lds_dwordx4 v[220:221], off
	v_lshl_add_u64 v[222:223], s[90:91], 0, v[130:131]
	s_mov_b32 m0, s89
	v_lshl_add_u64 v[224:225], s[42:43], 0, v[132:133]
	global_load_lds_dwordx4 v[222:223], off
	v_lshl_add_u64 v[222:223], s[90:91], 0, v[134:135]
	s_add_i32 m0, s89, 0x2000
	s_nop 0
	global_load_lds_dwordx4 v[222:223], off
	v_lshl_add_u64 v[222:223], s[42:43], 0, v[128:129]
	s_mov_b32 m0, s27
	s_nop 0
	global_load_lds_dwordx4 v[222:223], off
	s_mov_b32 m0, s29
	s_nop 0
	global_load_lds_dwordx4 v[224:225], off
	s_waitcnt vmcnt(8)
	s_waitcnt lgkmcnt(0)
	s_barrier
; #define PG8_STAGE(bufoff, gbase, voff) do { _Pragma("unroll") for (int _i = 0; _i < 2; ++_i) \
;         __builtin_amdgcn_global_load_lds((const unsigned*)((const char*)(gbase) + (voff)[_i]), (LAS unsigned*)(lds + (bufoff) + ldsw + _i * 8192), 16, 0, 0); } while (0)
; #define PG8_LDA(dst, b, h) do { _Pragma("unroll") for (int m = 0; m < 4; ++m) _Pragma("unroll") for (int k = 0; k < 2; ++k) dst[m][k] = *(const LAS bf16x8*)(lds + PG8_SA(b, h) + aoff + m * 2048 + k * 1024); } while (0)
; #define PG8_LDB(dst, b, h) do { _Pragma("unroll") for (int n = 0; n < 2; ++n) _Pragma("unroll") for (int k = 0; k < 2; ++k) dst[n][k] = *(const LAS bf16x8*)(lds + PG8_SB(b, h) + boff + n * 2048 + k * 1024); } while (0)
; #define PG8_MMA(ai, bj, At, Bt) do { __builtin_amdgcn_s_setprio(1); _Pragma("unroll") for (int m = 0; m < 4; ++m) _Pragma("unroll") for (int n = 0; n < 2; ++n) _Pragma("unroll") for (int k = 0; k < 2; ++k) \
;         acc[ai][bj][m][n] = __builtin_amdgcn_mfma_f32_16x16x32_bf16(Bt[n][k], At[m][k], acc[ai][bj][m][n], 0, 0, 0); __builtin_amdgcn_s_setprio(0); } while (0)
; #define PG8_WAIT_V(n) asm volatile("s_waitcnt vmcnt(" #n ")" ::: "memory")
; #define PG8_WAIT_L(n) asm volatile("s_waitcnt lgkmcnt(" #n ")" ::: "memory")
; #define PG8_BAR __builtin_amdgcn_s_barrier()
; #define PG8_SCHED __builtin_amdgcn_sched_barrier(0)
; template <class Epi>
; __device__ __forceinline__ void gemm_phase(LAS unsigned char* lds, const Gemm g, const StaticOrder& S, const Epi& E) {
;     ...
;             PG8_LDB(B0, 0, 0); PG8_LDB(B1, 0, 1); PG8_SCHED; PG8_LDA(At, 0, 0); PG8_STAGE(PG8_SA(1, 1), a1 + hstepA, voffA);
;             PG8_WAIT_V(8); PG8_WAIT_L(0); PG8_BAR; PG8_MMA(0, 0, At, B0); PG8_MMA(0, 1, At, B1); PG8_BAR; PG8_SCHED;
;             PG8_LDA(At, 0, 1); PG8_STAGE(PG8_SB(0, 0), b2, voffB); PG8_STAGE(PG8_SB(0, 1), b2 + hstepB, voffB); PG8_STAGE(PG8_SA(0, 0), a2, voffA);
;             PG8_WAIT_V(8); PG8_WAIT_L(0); PG8_BAR; PG8_MMA(1, 0, At, B0); PG8_MMA(1, 1, At, B1); PG8_BAR; PG8_SCHED;
;             PG8_LDB(B0, 1, 0); PG8_LDB(B1, 1, 1); PG8_SCHED; PG8_LDA(At, 1, 0); PG8_STAGE(PG8_SA(0, 1), a2 + hstepA, voffA);
;             PG8_WAIT_V(8); PG8_WAIT_L(0); PG8_BAR; PG8_MMA(0, 0, At, B0); PG8_MMA(0, 1, At, B1); PG8_BAR; PG8_SCHED;
	s_setprio 1
	s_waitcnt lgkmcnt(0)
	v_mfma_f32_16x16x32_bf16 v[60:63], v[146:149], v[184:187], v[60:63]
	v_mfma_f32_16x16x32_bf16 v[52:55], v[154:157], v[184:187], v[52:55]
	v_mfma_f32_16x16x32_bf16 v[44:47], v[146:149], v[196:199], v[44:47]
	v_mfma_f32_16x16x32_bf16 v[36:39], v[154:157], v[196:199], v[36:39]
	v_mfma_f32_16x16x32_bf16 v[28:31], v[146:149], v[204:207], v[28:31]
	v_mfma_f32_16x16x32_bf16 v[20:23], v[154:157], v[204:207], v[20:23]
	v_mfma_f32_16x16x32_bf16 v[12:15], v[146:149], v[212:215], v[12:15]
	v_mfma_f32_16x16x32_bf16 v[4:7], v[154:157], v[212:215], v[4:7]
	v_mfma_f32_16x16x32_bf16 v[60:63], v[150:153], v[188:191], v[60:63]
	v_mfma_f32_16x16x32_bf16 v[52:55], v[158:161], v[188:191], v[52:55]
	v_mfma_f32_16x16x32_bf16 v[44:47], v[150:153], v[200:203], v[44:47]
	v_mfma_f32_16x16x32_bf16 v[36:39], v[158:161], v[200:203], v[36:39]
	v_mfma_f32_16x16x32_bf16 v[28:31], v[150:153], v[208:211], v[28:31]
	v_mfma_f32_16x16x32_bf16 v[20:23], v[158:161], v[208:211], v[20:23]
	v_mfma_f32_16x16x32_bf16 v[12:15], v[150:153], v[216:219], v[12:15]
	v_mfma_f32_16x16x32_bf16 v[4:7], v[158:161], v[216:219], v[4:7]
	s_setprio 0
	s_setprio 1
	v_mfma_f32_16x16x32_bf16 v[56:59], v[168:171], v[184:187], v[56:59]
	v_mfma_f32_16x16x32_bf16 v[48:51], v[176:179], v[184:187], v[48:51]
	v_mfma_f32_16x16x32_bf16 v[40:43], v[168:171], v[196:199], v[40:43]
	v_mfma_f32_16x16x32_bf16 v[32:35], v[176:179], v[196:199], v[32:35]
	v_mfma_f32_16x16x32_bf16 v[24:27], v[168:171], v[204:207], v[24:27]
	v_mfma_f32_16x16x32_bf16 v[16:19], v[176:179], v[204:207], v[16:19]
	v_mfma_f32_16x16x32_bf16 v[8:11], v[168:171], v[212:215], v[8:11]
	v_mfma_f32_16x16x32_bf16 v[0:3], v[176:179], v[212:215], v[0:3]
	v_mfma_f32_16x16x32_bf16 v[56:59], v[172:175], v[188:191], v[56:59]
	v_mfma_f32_16x16x32_bf16 v[48:51], v[180:183], v[188:191], v[48:51]
	v_mfma_f32_16x16x32_bf16 v[40:43], v[172:175], v[200:203], v[40:43]
	v_mfma_f32_16x16x32_bf16 v[32:35], v[180:183], v[200:203], v[32:35]
	v_mfma_f32_16x16x32_bf16 v[24:27], v[172:175], v[208:211], v[24:27]
	v_mfma_f32_16x16x32_bf16 v[16:19], v[180:183], v[208:211], v[16:19]
	v_mfma_f32_16x16x32_bf16 v[8:11], v[172:175], v[216:219], v[8:11]
	v_mfma_f32_16x16x32_bf16 v[0:3], v[180:183], v[216:219], v[0:3]
	s_setprio 0
	s_barrier
	s_add_i32 s89, 0, 0x18000
	s_add_i32 s90, 0, 0x1c000
	v_add_u32_e32 v158, s89, v163
	v_add_u32_e32 v167, s90, v163
	ds_read_b128 v[146:149], v158
	ds_read_b128 v[150:153], v158 offset:1024
	ds_read_b128 v[154:157], v158 offset:2048
	ds_read_b128 v[158:161], v158 offset:3072
	ds_read_b128 v[168:171], v167
	ds_read_b128 v[172:175], v167 offset:1024
	ds_read_b128 v[176:179], v167 offset:2048
	ds_read_b128 v[180:183], v167 offset:3072
	s_add_u32 s42, s42, 0x40000
	s_addc_u32 s43, s43, 0
	s_mov_b32 m0, s31
	v_lshl_add_u64 v[226:227], s[42:43], 0, v[128:129]
	ds_read_b128 v[184:187], v166 offset:32768
	ds_read_b128 v[188:191], v166 offset:33792
	ds_read_b128 v[196:199], v166 offset:34816
	ds_read_b128 v[200:203], v166 offset:35840
	ds_read_b128 v[204:207], v166 offset:36864
	ds_read_b128 v[208:211], v166 offset:37888
	ds_read_b128 v[212:215], v166 offset:38912
	ds_read_b128 v[216:219], v166 offset:39936
	global_load_lds_dwordx4 v[226:227], off
	v_lshl_add_u64 v[226:227], s[42:43], 0, v[132:133]
	s_mov_b32 m0, s35
	s_nop 0
	global_load_lds_dwordx4 v[226:227], off
	s_waitcnt vmcnt(8)
	s_waitcnt lgkmcnt(0)
	s_barrier
	s_setprio 1
	s_waitcnt lgkmcnt(0)
	v_mfma_f32_16x16x32_bf16 v[124:127], v[146:149], v[184:187], v[124:127]
	v_mfma_f32_16x16x32_bf16 v[116:119], v[154:157], v[184:187], v[116:119]
	v_mfma_f32_16x16x32_bf16 v[108:111], v[146:149], v[196:199], v[108:111]
	v_mfma_f32_16x16x32_bf16 v[100:103], v[154:157], v[196:199], v[100:103]
	v_mfma_f32_16x16x32_bf16 v[92:95], v[146:149], v[204:207], v[92:95]
	v_mfma_f32_16x16x32_bf16 v[84:87], v[154:157], v[204:207], v[84:87]
	v_mfma_f32_16x16x32_bf16 v[76:79], v[146:149], v[212:215], v[76:79]
	v_mfma_f32_16x16x32_bf16 v[68:71], v[154:157], v[212:215], v[68:71]
	v_mfma_f32_16x16x32_bf16 v[124:127], v[150:153], v[188:191], v[124:127]
	v_mfma_f32_16x16x32_bf16 v[116:119], v[158:161], v[188:191], v[116:119]
	v_mfma_f32_16x16x32_bf16 v[108:111], v[150:153], v[200:203], v[108:111]
	v_mfma_f32_16x16x32_bf16 v[100:103], v[158:161], v[200:203], v[100:103]
	v_mfma_f32_16x16x32_bf16 v[92:95], v[150:153], v[208:211], v[92:95]
	v_mfma_f32_16x16x32_bf16 v[84:87], v[158:161], v[208:211], v[84:87]
	v_mfma_f32_16x16x32_bf16 v[76:79], v[150:153], v[216:219], v[76:79]
	v_mfma_f32_16x16x32_bf16 v[68:71], v[158:161], v[216:219], v[68:71]
	s_setprio 0
	s_setprio 1
	v_mfma_f32_16x16x32_bf16 v[120:123], v[168:171], v[184:187], v[120:123]
	v_mfma_f32_16x16x32_bf16 v[112:115], v[176:179], v[184:187], v[112:115]
	v_mfma_f32_16x16x32_bf16 v[104:107], v[168:171], v[196:199], v[104:107]
	v_mfma_f32_16x16x32_bf16 v[96:99], v[176:179], v[196:199], v[96:99]
	v_mfma_f32_16x16x32_bf16 v[88:91], v[168:171], v[204:207], v[88:91]
	v_mfma_f32_16x16x32_bf16 v[80:83], v[176:179], v[204:207], v[80:83]
	v_mfma_f32_16x16x32_bf16 v[72:75], v[168:171], v[212:215], v[72:75]
	v_mfma_f32_16x16x32_bf16 v[64:67], v[176:179], v[212:215], v[64:67]
	v_mfma_f32_16x16x32_bf16 v[120:123], v[172:175], v[188:191], v[120:123]
	v_mfma_f32_16x16x32_bf16 v[112:115], v[180:183], v[188:191], v[112:115]
	v_mfma_f32_16x16x32_bf16 v[104:107], v[172:175], v[200:203], v[104:107]
	v_mfma_f32_16x16x32_bf16 v[96:99], v[180:183], v[200:203], v[96:99]
	v_mfma_f32_16x16x32_bf16 v[88:91], v[172:175], v[208:211], v[88:91]
	v_mfma_f32_16x16x32_bf16 v[80:83], v[180:183], v[208:211], v[80:83]
	v_mfma_f32_16x16x32_bf16 v[72:75], v[172:175], v[216:219], v[72:75]
	v_mfma_f32_16x16x32_bf16 v[64:67], v[180:183], v[216:219], v[64:67]
	s_setprio 0
	s_barrier
; #define PG8_STAGE(bufoff, gbase, voff) do { _Pragma("unroll") for (int _i = 0; _i < 2; ++_i) \
;         __builtin_amdgcn_global_load_lds((const unsigned*)((const char*)(gbase) + (voff)[_i]), (LAS unsigned*)(lds + (bufoff) + ldsw + _i * 8192), 16, 0, 0); } while (0)
; #define PG8_LDA(dst, b, h) do { _Pragma("unroll") for (int m = 0; m < 4; ++m) _Pragma("unroll") for (int k = 0; k < 2; ++k) dst[m][k] = *(const LAS bf16x8*)(lds + PG8_SA(b, h) + aoff + m * 2048 + k * 1024); } while (0)
; #define PG8_LDB(dst, b, h) do { _Pragma("unroll") for (int n = 0; n < 2; ++n) _Pragma("unroll") for (int k = 0; k < 2; ++k) dst[n][k] = *(const LAS bf16x8*)(lds + PG8_SB(b, h) + boff + n * 2048 + k * 1024); } while (0)
; template <class Epi>
; __device__ __forceinline__ void gemm_phase(LAS unsigned char* lds, const Gemm g, const StaticOrder& S, const Epi& E) {
;     ...
;         for (int t = hf * nth; t < (hf + 1) * nth; t += 2) {
;             const bool last = (t == nt - 2);
;             const char* a1 = cA + (size_t)(t + 1) * kstep;
;             const char* a2 = last ? nA : cA + (size_t)(t + 2) * kstep; const char* b2 = last ? nB : cB + (size_t)(t + 2) * kstep;
;             const char* a3 = a2 + kstep; const char* b3 = b2 + kstep;
;             PG8_LDB(B0, 0, 0); PG8_LDB(B1, 0, 1); PG8_SCHED; PG8_LDA(At, 0, 0); PG8_STAGE(PG8_SA(1, 1), a1 + hstepA, voffA);
;             PG8_WAIT_V(8); PG8_WAIT_L(0); PG8_BAR; PG8_MMA(0, 0, At, B0); PG8_MMA(0, 1, At, B1); PG8_BAR; PG8_SCHED;
;             PG8_LDA(At, 0, 1); PG8_STAGE(PG8_SB(0, 0), b2, voffB); PG8_STAGE(PG8_SB(0, 1), b2 + hstepB, voffB); PG8_STAGE(PG8_SA(0, 0), a2, voffA);
;             PG8_WAIT_V(8); PG8_WAIT_L(0); PG8_BAR; PG8_MMA(1, 0, At, B0); PG8_MMA(1, 1, At, B1); PG8_BAR; PG8_SCHED;
;             PG8_LDB(B0, 1, 0); PG8_LDB(B1, 1, 1); PG8_SCHED; PG8_LDA(At, 1, 0); PG8_STAGE(PG8_SA(0, 1), a2 + hstepA, voffA);
;             PG8_WAIT_V(8); PG8_WAIT_L(0); PG8_BAR; PG8_MMA(0, 0, At, B0); PG8_MMA(0, 1, At, B1); PG8_BAR; PG8_SCHED;
;             PG8_LDA(At, 1, 1); PG8_STAGE(PG8_SB(1, 0), b3, voffB); PG8_STAGE(PG8_SB(1, 1), b3 + hstepB, voffB); PG8_STAGE(PG8_SA(1, 0), a3, voffA);
;             PG8_WAIT_V(8); PG8_WAIT_L(0); PG8_BAR; PG8_MMA(1, 0, At, B0); PG8_MMA(1, 1, At, B1); PG8_BAR; PG8_SCHED;
;         }
;         if constexpr (Epi::MID) { if (hf == 0) E.mid(acc, cur, wr, wc, fr, fq); }
;         }
;         if (wr == 0) PG8_BAR;
	s_add_i32 s42, s89, s3
	v_lshl_add_u64 v[192:193], v[192:193], 0, s[22:23]
	s_mov_b32 m0, s42
	ds_read_b128 v[184:187], v166 offset:49152
	ds_read_b128 v[188:191], v166 offset:50176
	ds_read_b128 v[196:199], v166 offset:51200
	ds_read_b128 v[200:203], v166 offset:52224
	ds_read_b128 v[204:207], v166 offset:53248
	ds_read_b128 v[208:211], v166 offset:54272
	ds_read_b128 v[212:215], v166 offset:55296
	ds_read_b128 v[216:219], v166 offset:56320
	global_load_lds_dwordx4 v[192:193], off
	s_add_i32 m0, s42, 0x2000
	s_add_u32 s42, s86, 0x40080
	v_lshl_add_u64 v[192:193], v[220:221], 0, s[22:23]
	s_addc_u32 s43, s87, 0
	s_add_i32 s86, s90, s3
	global_load_lds_dwordx4 v[192:193], off
	v_lshl_add_u64 v[192:193], s[42:43], 0, v[130:131]
	s_mov_b32 m0, s86
	s_nop 0
	global_load_lds_dwordx4 v[192:193], off
	v_lshl_add_u64 v[192:193], s[42:43], 0, v[134:135]
	s_add_i32 m0, s86, 0x2000
	s_nop 0
	global_load_lds_dwordx4 v[192:193], off
	v_lshl_add_u64 v[192:193], v[222:223], 0, s[22:23]
	s_mov_b32 m0, s37
	s_nop 0
	global_load_lds_dwordx4 v[192:193], off
	v_lshl_add_u64 v[192:193], v[224:225], 0, s[22:23]
	s_mov_b32 m0, s51
	s_nop 0
	global_load_lds_dwordx4 v[192:193], off
	s_waitcnt vmcnt(8)
	s_waitcnt lgkmcnt(0)
	s_barrier
	s_setprio 1
	s_waitcnt lgkmcnt(0)
	v_mfma_f32_16x16x32_bf16 v[60:63], v[146:149], v[184:187], v[60:63]
	v_mfma_f32_16x16x32_bf16 v[52:55], v[154:157], v[184:187], v[52:55]
	v_mfma_f32_16x16x32_bf16 v[44:47], v[146:149], v[196:199], v[44:47]
	v_mfma_f32_16x16x32_bf16 v[36:39], v[154:157], v[196:199], v[36:39]
	v_mfma_f32_16x16x32_bf16 v[28:31], v[146:149], v[204:207], v[28:31]
	v_mfma_f32_16x16x32_bf16 v[20:23], v[154:157], v[204:207], v[20:23]
	v_mfma_f32_16x16x32_bf16 v[12:15], v[146:149], v[212:215], v[12:15]
	v_mfma_f32_16x16x32_bf16 v[4:7], v[154:157], v[212:215], v[4:7]
	v_mfma_f32_16x16x32_bf16 v[60:63], v[150:153], v[188:191], v[60:63]
	v_mfma_f32_16x16x32_bf16 v[52:55], v[158:161], v[188:191], v[52:55]
	v_mfma_f32_16x16x32_bf16 v[44:47], v[150:153], v[200:203], v[44:47]
	v_mfma_f32_16x16x32_bf16 v[36:39], v[158:161], v[200:203], v[36:39]
	v_mfma_f32_16x16x32_bf16 v[28:31], v[150:153], v[208:211], v[28:31]
	v_mfma_f32_16x16x32_bf16 v[20:23], v[158:161], v[208:211], v[20:23]
	v_mfma_f32_16x16x32_bf16 v[12:15], v[150:153], v[216:219], v[12:15]
	v_mfma_f32_16x16x32_bf16 v[4:7], v[158:161], v[216:219], v[4:7]
	s_setprio 0
	s_setprio 1
	v_mfma_f32_16x16x32_bf16 v[56:59], v[168:171], v[184:187], v[56:59]
	v_mfma_f32_16x16x32_bf16 v[48:51], v[176:179], v[184:187], v[48:51]
	v_mfma_f32_16x16x32_bf16 v[40:43], v[168:171], v[196:199], v[40:43]
	v_mfma_f32_16x16x32_bf16 v[32:35], v[176:179], v[196:199], v[32:35]
	v_mfma_f32_16x16x32_bf16 v[24:27], v[168:171], v[204:207], v[24:27]
	v_mfma_f32_16x16x32_bf16 v[16:19], v[176:179], v[204:207], v[16:19]
	v_mfma_f32_16x16x32_bf16 v[8:11], v[168:171], v[212:215], v[8:11]
	v_mfma_f32_16x16x32_bf16 v[0:3], v[176:179], v[212:215], v[0:3]
	v_mfma_f32_16x16x32_bf16 v[56:59], v[172:175], v[188:191], v[56:59]
	v_mfma_f32_16x16x32_bf16 v[48:51], v[180:183], v[188:191], v[48:51]
	v_mfma_f32_16x16x32_bf16 v[40:43], v[172:175], v[200:203], v[40:43]
	v_mfma_f32_16x16x32_bf16 v[32:35], v[180:183], v[200:203], v[32:35]
	v_mfma_f32_16x16x32_bf16 v[24:27], v[172:175], v[208:211], v[24:27]
	v_mfma_f32_16x16x32_bf16 v[16:19], v[180:183], v[208:211], v[16:19]
	v_mfma_f32_16x16x32_bf16 v[8:11], v[172:175], v[216:219], v[8:11]
	v_mfma_f32_16x16x32_bf16 v[0:3], v[180:183], v[216:219], v[0:3]
	s_setprio 0
	s_barrier
	s_add_i32 s88, s88, 2
	s_add_u32 s8, s8, 0x100
	s_addc_u32 s9, s9, 0
	s_add_u32 s77, s77, 0x100
	s_addc_u32 s79, s79, 0
	s_cmp_gt_u32 s88, 13
	s_cbranch_scc0 .LBB0_160
	s_and_b64 vcc, exec, s[24:25]
	s_cbranch_vccz .LBB0_163
.LBB0_163:
	s_lshl_b32 s7, s6, 8
	v_add_u32_e32 v146, s7, v162
	s_cmp_gt_i32 s84, 7
	s_mov_b64 s[8:9], -1
	s_cbranch_scc1 .LBB0_166
	s_and_b64 vcc, exec, s[8:9]
	s_cbranch_vccnz .LBB0_411

; __device__ __forceinline__ unsigned cvt_pk_bf16(float lo, float hi) { unsigned r; asm volatile("v_cvt_pk_bf16_f32 %0, %1, %2" : "=v"(r) : "v"(lo), "v"(hi)); return r; }
; __device__ __forceinline__ f32x4 gelu4(f32x4 v) { f32x2 a = gelu_pk((f32x2){v[0], v[1]}), b = gelu_pk((f32x2){v[2], v[3]}); return (f32x4){a.x, a.y, b.x, b.y}; }
; __device__ __forceinline__ f32x4 sigm4(f32x4 v) { return (f32x4){sigmoid_f(v[0]), sigmoid_f(v[1]), sigmoid_f(v[2]), sigmoid_f(v[3])}; }
; __device__ __forceinline__ f32x4 silu4(f32x4 v) { return v * sigm4(v); }
;     __device__ __forceinline__ void operator()(const f32x4 (&acc)[2][2][4][2], const pg8::Unit& u, int wr, int wc, int fr, int fq) const {
;     ...
;             const size_t rterm0 = headmajor ? (size_t)bidx * 4 * SEQ + t0 : (size_t)row0;
;             bf16_t* base = PJ + dst + wc * 32 + 8 * fq;
; #pragma unroll
;             for (int ai = 0; ai < 2; ++ai)
; #pragma unroll
;                 for (int m = 0; m < 4; ++m) {
;                     bf16_t* rowp = base + (rterm0 + ai * 128 + m * 16) * ld;
; #pragma unroll
;                     for (int bj = 0; bj < 2; ++bj) {
;                         f32x4 v0 = acc[ai][bj][m][0], v1 = acc[ai][bj][m][1];
;                         if (act == 5) { v0 = sigm4(v0); v1 = sigm4(v1);
;                             if (bj == 0) { const f32x4 b0 = sigm4(acc[ai][1][m][0]), b1 = sigm4(acc[ai][1][m][1]);
; #pragma unroll
;                                 for (int e = 0; e < 4; ++e) { v0[e] *= __builtin_amdgcn_rcpf(fmaxf(b0[e], 1e-20f)); v1[e] *= __builtin_amdgcn_rcpf(fmaxf(b1[e], 1e-20f)); } } }
;                         else if (act == 1) { v0 = gelu4(v0); v1 = gelu4(v1); }
;                         else if (act == 2) { v0 = silu4(v0); v1 = silu4(v1); }
;                         else if (act == 3) { v0 = sigm4(v0); v1 = sigm4(v1); }
;                         else if (act == 4) { v0 = v0 * 0.08838834764831845f; v1 = v1 * 0.08838834764831845f; }
;                         u32x4 w; w.x = cvt_pk_bf16(v0[0], v0[1]); w.y = cvt_pk_bf16(v0[2], v0[3]); w.z = cvt_pk_bf16(v1[0], v1[1]); w.w = cvt_pk_bf16(v1[2], v1[3]);
;                         __builtin_nontemporal_store(w, (u32x4*)(rowp + (size_t)bj * bjs));
.LBB0_200:
	v_lshl_add_u64 v[148:149], s[8:9], 1, v[136:137]
	v_mul_lo_u32 v147, v151, s94
	v_mul_lo_u32 v152, v150, s95
	v_mad_u64_u32 v[150:151], s[8:9], v150, s94, 0
	v_add3_u32 v151, v151, v152, v147
	v_cndmask_b32_e64 v147, 0, 1, s[6:7]
	v_cmp_ne_u32_e64 s[8:9], 1, v147
	v_cndmask_b32_e64 v147, 0, 1, s[92:93]
	v_lshl_add_u64 v[152:153], v[150:151], 1, v[148:149]
	v_cvt_pk_bf16_f32 v154, v154, v155
	v_cvt_pk_bf16_f32 v155, v156, v157
	v_cvt_pk_bf16_f32 v156, v158, v159
	v_cvt_pk_bf16_f32 v157, v160, v161
	s_mov_b64 s[16:17], -1
	s_andn2_b64 vcc, exec, s[6:7]
	v_cmp_ne_u32_e64 s[6:7], 1, v147
	global_store_dwordx4 v[152:153], v[154:157], off nt
	s_cmp_lg_u64 s[24:25], 0
	s_cbranch_scc0 .Lepi_nb_a
	s_barrier
.Lepi_nb_a:
	s_cbranch_vccnz .LBB0_212
	s_and_b64 vcc, exec, s[6:7]
	s_cbranch_vccnz .LBB0_209
	s_andn2_b64 vcc, exec, s[90:91]
	s_cbranch_vccnz .LBB0_206
	s_andn2_b64 vcc, exec, s[88:89]
	v_mov_b32_e32 v161, v115
	v_mov_b32_e32 v160, v114
	v_mov_b32_e32 v159, v113
	v_mov_b32_e32 v158, v112
	v_mov_b32_e32 v157, v123
	v_mov_b32_e32 v156, v122
	v_mov_b32_e32 v155, v121
	v_mov_b32_e32 v154, v120
	s_cbranch_vccnz .LBB0_205
	v_pk_mul_f32 v[156:157], v[122:123], s[26:27] op_sel_hi:[1,0]
	v_pk_mul_f32 v[154:155], v[120:121], s[26:27] op_sel_hi:[1,0]
	v_pk_mul_f32 v[160:161], v[114:115], s[26:27] op_sel_hi:[1,0]
	v_pk_mul_f32 v[158:159], v[112:113], s[26:27] op_sel_hi:[1,0]

; __device__ __forceinline__ unsigned cvt_pk_bf16(float lo, float hi) { unsigned r; asm volatile("v_cvt_pk_bf16_f32 %0, %1, %2" : "=v"(r) : "v"(lo), "v"(hi)); return r; }
; __device__ __forceinline__ float sigmoid_f(float x) { return __builtin_amdgcn_rcpf(1.0f + __builtin_amdgcn_exp2f(-1.44269504f * x)); }
; __device__ __forceinline__ f32x2 gelu_pk(f32x2 v) {
;     const f32x2 av = __builtin_elementwise_abs(v), d = av * 0.2316418882f + 1.0f;
;     f32x2 t; t.x = __builtin_amdgcn_rcpf(d.x); t.y = __builtin_amdgcn_rcpf(d.y);
;     f32x2 q = t * 0.5307027145f + (-0.7265760135f); q = q * t + 0.7107068705f; q = q * t + (-0.142248368f); q = q * t + 0.127414796f; q = q * t;
;     const f32x2 s = (v * v) * (-0.72134752044f);
;     f32x2 e; e.x = __builtin_amdgcn_exp2f(s.x); e.y = __builtin_amdgcn_exp2f(s.y);
;     const f32x2 m = v * (q * e), r = v - m;
;     f32x2 o; o.x = v.x < 0.f ? m.x : r.x; o.y = v.y < 0.f ? m.y : r.y; return o;
; }
; __device__ __forceinline__ f32x4 gelu4(f32x4 v) { f32x2 a = gelu_pk((f32x2){v[0], v[1]}), b = gelu_pk((f32x2){v[2], v[3]}); return (f32x4){a.x, a.y, b.x, b.y}; }
; __device__ __forceinline__ f32x4 sigm4(f32x4 v) { return (f32x4){sigmoid_f(v[0]), sigmoid_f(v[1]), sigmoid_f(v[2]), sigmoid_f(v[3])}; }
; __device__ __forceinline__ f32x4 silu4(f32x4 v) { return v * sigm4(v); }
;     __device__ __forceinline__ void operator()(const f32x4 (&acc)[2][2][4][2], const pg8::Unit& u, int wr, int wc, int fr, int fq) const {
;     ...
;         if (pn < 8) {
;             bf16_t* base = PJ + T_P + 128 * pn + wc * 32 + 8 * fq;
; #pragma unroll
;             for (int ai = 0; ai < 2; ++ai)
; #pragma unroll
;                 for (int m = 0; m < 4; ++m) {
;                     bf16_t* rowp = base + (size_t)(row0 + ai * 128 + m * 16) * 1024;
;                     const f32x4 v0 = gelu4(acc[ai][0][m][0]) * silu4(acc[ai][1][m][0]), v1 = gelu4(acc[ai][0][m][1]) * silu4(acc[ai][1][m][1]);
;                     u32x4 w; w.x = cvt_pk_bf16(v0[0], v0[1]); w.y = cvt_pk_bf16(v0[2], v0[3]); w.z = cvt_pk_bf16(v1[0], v1[1]); w.w = cvt_pk_bf16(v1[2], v1[3]);
;                     __builtin_nontemporal_store(w, (u32x4*)rowp);
;                 }
.LBB0_411:
	v_and_b32_e32 v149, 0x7fffffff, v125
	v_and_b32_e32 v148, 0x7fffffff, v124
	v_pk_fma_f32 v[148:149], v[148:149], s[28:29], 1.0 op_sel_hi:[1,0,0]
	v_mov_b64_e32 v[150:151], s[34:35]
	v_rcp_f32_e32 v154, v148
	v_rcp_f32_e32 v155, v149
	v_pk_mul_f32 v[158:159], v[124:125], v[124:125]
	v_and_b32_e32 v161, 0x7fffffff, v127
	v_pk_mul_f32 v[158:159], v[158:159], s[74:75] op_sel_hi:[1,0]
	v_pk_fma_f32 v[156:157], v[154:155], s[30:31], v[150:151] op_sel_hi:[1,0,0]
	v_exp_f32_e32 v158, v158
	v_pk_fma_f32 v[156:157], v[154:155], v[156:157], s[36:37] op_sel_hi:[1,1,0]
	v_exp_f32_e32 v159, v159
	v_pk_fma_f32 v[156:157], v[154:155], v[156:157], s[50:51] op_sel_hi:[1,1,0]
	v_and_b32_e32 v160, 0x7fffffff, v126
	v_pk_fma_f32 v[156:157], v[154:155], v[156:157], s[72:73] op_sel_hi:[1,1,0]
	v_pk_fma_f32 v[160:161], v[160:161], s[28:29], 1.0 op_sel_hi:[1,0,0]
	v_pk_mul_f32 v[154:155], v[154:155], v[156:157]
	v_rcp_f32_e32 v160, v160
	v_rcp_f32_e32 v161, v161
	v_pk_mul_f32 v[154:155], v[158:159], v[154:155]
	v_cmp_gt_f32_e32 vcc, 0, v124
	v_pk_mul_f32 v[158:159], v[124:125], v[154:155]
	v_pk_fma_f32 v[154:155], v[124:125], v[154:155], v[124:125] neg_lo:[1,0,0] neg_hi:[1,0,0]
	v_pk_mul_f32 v[156:157], v[126:127], v[126:127]
	v_cndmask_b32_e32 v124, v154, v158, vcc
	v_cmp_gt_f32_e32 vcc, 0, v125
	v_pk_mul_f32 v[156:157], v[156:157], s[74:75] op_sel_hi:[1,0]
	v_ashrrev_i32_e32 v147, 31, v146
	v_cndmask_b32_e32 v125, v155, v159, vcc
	v_pk_fma_f32 v[154:155], v[160:161], s[30:31], v[150:151] op_sel_hi:[1,0,0]
	v_exp_f32_e32 v156, v156
	v_pk_fma_f32 v[154:155], v[160:161], v[154:155], s[36:37] op_sel_hi:[1,1,0]
	v_exp_f32_e32 v157, v157
	v_pk_fma_f32 v[154:155], v[160:161], v[154:155], s[50:51] op_sel_hi:[1,1,0]
	v_lshlrev_b64 v[148:149], 11, v[146:147]
	v_pk_fma_f32 v[154:155], v[160:161], v[154:155], s[72:73] op_sel_hi:[1,1,0]
	v_cmp_gt_f32_e32 vcc, 0, v126
	v_pk_mul_f32 v[154:155], v[160:161], v[154:155]
	v_mul_f32_e32 v147, 0xbfb8aa3b, v120
	v_pk_mul_f32 v[154:155], v[156:157], v[154:155]
	v_exp_f32_e32 v147, v147
	v_pk_mul_f32 v[156:157], v[126:127], v[154:155]
	v_pk_fma_f32 v[154:155], v[126:127], v[154:155], v[126:127] neg_lo:[1,0,0] neg_hi:[1,0,0]
	s_lshl_b32 s6, s84, 7
	v_cndmask_b32_e32 v126, v154, v156, vcc
	v_mul_f32_e32 v154, 0xbfb8aa3b, v121
	v_exp_f32_e32 v156, v154
	v_cmp_gt_f32_e32 vcc, 0, v127
	v_add_f32_e32 v147, 1.0, v147
	v_rcp_f32_e32 v154, v147
	v_cndmask_b32_e32 v127, v155, v157, vcc
	v_mul_f32_e32 v155, 0xbfb8aa3b, v122
	v_add_f32_e32 v147, 1.0, v156
	v_exp_f32_e32 v156, v155
	v_mul_f32_e32 v155, 0xbfb8aa3b, v123
	v_exp_f32_e32 v157, v155
	v_rcp_f32_e32 v155, v147
	v_add_f32_e32 v147, 1.0, v156
	v_rcp_f32_e32 v156, v147
	v_add_f32_e32 v147, 1.0, v157
	v_rcp_f32_e32 v157, v147
	v_pk_mul_f32 v[120:121], v[120:121], v[154:155]
	v_and_b32_e32 v155, 0x7fffffff, v117
	v_and_b32_e32 v154, 0x7fffffff, v116
	v_pk_fma_f32 v[154:155], v[154:155], s[28:29], 1.0 op_sel_hi:[1,0,0]
	v_pk_mul_f32 v[122:123], v[122:123], v[156:157]
	v_rcp_f32_e32 v154, v154
	v_rcp_f32_e32 v155, v155
	v_pk_mul_f32 v[122:123], v[126:127], v[122:123]
	v_pk_mul_f32 v[126:127], v[116:117], v[116:117]
	v_pk_mul_f32 v[120:121], v[124:125], v[120:121]
	v_pk_fma_f32 v[124:125], v[154:155], s[30:31], v[150:151] op_sel_hi:[1,0,0]
	v_pk_mul_f32 v[126:127], v[126:127], s[74:75] op_sel_hi:[1,0]
	v_pk_fma_f32 v[124:125], v[154:155], v[124:125], s[36:37] op_sel_hi:[1,1,0]
	v_exp_f32_e32 v126, v126
	v_exp_f32_e32 v127, v127
	v_pk_fma_f32 v[124:125], v[154:155], v[124:125], s[50:51] op_sel_hi:[1,1,0]
	v_and_b32_e32 v157, 0x7fffffff, v119
	v_and_b32_e32 v156, 0x7fffffff, v118
	v_pk_fma_f32 v[124:125], v[154:155], v[124:125], s[72:73] op_sel_hi:[1,1,0]
	v_pk_fma_f32 v[156:157], v[156:157], s[28:29], 1.0 op_sel_hi:[1,0,0]
	v_pk_mul_f32 v[124:125], v[154:155], v[124:125]
	v_rcp_f32_e32 v156, v156
	v_rcp_f32_e32 v157, v157
	v_pk_mul_f32 v[124:125], v[126:127], v[124:125]
	v_cmp_gt_f32_e32 vcc, 0, v116
	v_pk_mul_f32 v[126:127], v[116:117], v[124:125]
	v_pk_fma_f32 v[124:125], v[116:117], v[124:125], v[116:117] neg_lo:[1,0,0] neg_hi:[1,0,0]
	v_pk_mul_f32 v[154:155], v[118:119], v[118:119]
	v_cndmask_b32_e32 v116, v124, v126, vcc
	v_cmp_gt_f32_e32 vcc, 0, v117
	v_mul_f32_e32 v147, 0xbfb8aa3b, v112
	v_exp_f32_e32 v147, v147
	v_cndmask_b32_e32 v117, v125, v127, vcc
	v_pk_fma_f32 v[124:125], v[156:157], s[30:31], v[150:151] op_sel_hi:[1,0,0]
	v_pk_mul_f32 v[126:127], v[154:155], s[74:75] op_sel_hi:[1,0]
	v_pk_fma_f32 v[124:125], v[156:157], v[124:125], s[36:37] op_sel_hi:[1,1,0]
	v_exp_f32_e32 v126, v126
	v_exp_f32_e32 v127, v127
	v_pk_fma_f32 v[124:125], v[156:157], v[124:125], s[50:51] op_sel_hi:[1,1,0]
	v_mul_f32_e32 v154, 0xbfb8aa3b, v113
	v_pk_fma_f32 v[124:125], v[156:157], v[124:125], s[72:73] op_sel_hi:[1,1,0]
	v_cmp_gt_f32_e32 vcc, 0, v118
	v_pk_mul_f32 v[124:125], v[156:157], v[124:125]
	v_exp_f32_e32 v155, v154
	v_pk_mul_f32 v[124:125], v[126:127], v[124:125]
	s_ashr_i32 s7, s6, 31
	v_pk_mul_f32 v[126:127], v[118:119], v[124:125]
	v_pk_fma_f32 v[124:125], v[118:119], v[124:125], v[118:119] neg_lo:[1,0,0] neg_hi:[1,0,0]
	v_lshl_add_u64 v[152:153], s[6:7], 1, v[136:137]
	v_cndmask_b32_e32 v118, v124, v126, vcc
	v_mul_f32_e32 v126, 0xbfb8aa3b, v114
	v_add_f32_e32 v124, 1.0, v147
	v_exp_f32_e32 v126, v126
	v_mul_f32_e32 v147, 0xbfb8aa3b, v115
	v_exp_f32_e32 v147, v147
	v_rcp_f32_e32 v154, v124
	v_add_f32_e32 v124, 1.0, v155
	v_rcp_f32_e32 v155, v124
	v_add_f32_e32 v124, 1.0, v126
	v_rcp_f32_e32 v156, v124
	v_add_f32_e32 v124, 1.0, v147
	v_rcp_f32_e32 v157, v124
	v_cmp_gt_f32_e32 vcc, 0, v119
	v_pk_mul_f32 v[112:113], v[112:113], v[154:155]
	v_lshl_add_u64 v[148:149], v[152:153], 0, v[148:149]
	v_cndmask_b32_e32 v119, v125, v127, vcc
	v_pk_mul_f32 v[114:115], v[114:115], v[156:157]
	v_cmp_gt_f32_e32 vcc, 0, v108
	v_pk_mul_f32 v[118:119], v[118:119], v[114:115]
	v_pk_mul_f32 v[114:115], v[116:117], v[112:113]
	v_cvt_pk_bf16_f32 v112, v120, v121
	v_cvt_pk_bf16_f32 v113, v122, v123
	v_and_b32_e32 v121, 0x7fffffff, v111
	v_cvt_pk_bf16_f32 v114, v114, v115
	v_cvt_pk_bf16_f32 v115, v118, v119
	global_store_dwordx4 v[148:149], v[112:115], off nt
	s_cmp_lg_u64 s[24:25], 0
	s_cbranch_scc0 .Lepi_nb_b
	s_barrier
; __device__ __forceinline__ unsigned cvt_pk_bf16(float lo, float hi) { unsigned r; asm volatile("v_cvt_pk_bf16_f32 %0, %1, %2" : "=v"(r) : "v"(lo), "v"(hi)); return r; }
; __device__ __forceinline__ float sigmoid_f(float x) { return __builtin_amdgcn_rcpf(1.0f + __builtin_amdgcn_exp2f(-1.44269504f * x)); }
; __device__ __forceinline__ f32x2 gelu_pk(f32x2 v) {
;     const f32x2 av = __builtin_elementwise_abs(v), d = av * 0.2316418882f + 1.0f;
;     f32x2 t; t.x = __builtin_amdgcn_rcpf(d.x); t.y = __builtin_amdgcn_rcpf(d.y);
;     f32x2 q = t * 0.5307027145f + (-0.7265760135f); q = q * t + 0.7107068705f; q = q * t + (-0.142248368f); q = q * t + 0.127414796f; q = q * t;
;     const f32x2 s = (v * v) * (-0.72134752044f);
;     f32x2 e; e.x = __builtin_amdgcn_exp2f(s.x); e.y = __builtin_amdgcn_exp2f(s.y);
;     const f32x2 m = v * (q * e), r = v - m;
;     f32x2 o; o.x = v.x < 0.f ? m.x : r.x; o.y = v.y < 0.f ? m.y : r.y; return o;
; }
; __device__ __forceinline__ f32x4 gelu4(f32x4 v) { f32x2 a = gelu_pk((f32x2){v[0], v[1]}), b = gelu_pk((f32x2){v[2], v[3]}); return (f32x4){a.x, a.y, b.x, b.y}; }
; __device__ __forceinline__ f32x4 sigm4(f32x4 v) { return (f32x4){sigmoid_f(v[0]), sigmoid_f(v[1]), sigmoid_f(v[2]), sigmoid_f(v[3])}; }
; __device__ __forceinline__ f32x4 silu4(f32x4 v) { return v * sigm4(v); }
;     __device__ __forceinline__ void operator()(const f32x4 (&acc)[2][2][4][2], const pg8::Unit& u, int wr, int wc, int fr, int fq) const {
;     ...
;         if (pn < 8) {
;             bf16_t* base = PJ + T_P + 128 * pn + wc * 32 + 8 * fq;
; #pragma unroll
;             for (int ai = 0; ai < 2; ++ai)
; #pragma unroll
;                 for (int m = 0; m < 4; ++m) {
;                     bf16_t* rowp = base + (size_t)(row0 + ai * 128 + m * 16) * 1024;
;                     const f32x4 v0 = gelu4(acc[ai][0][m][0]) * silu4(acc[ai][1][m][0]), v1 = gelu4(acc[ai][0][m][1]) * silu4(acc[ai][1][m][1]);
;                     u32x4 w; w.x = cvt_pk_bf16(v0[0], v0[1]); w.y = cvt_pk_bf16(v0[2], v0[3]); w.z = cvt_pk_bf16(v1[0], v1[1]); w.w = cvt_pk_bf16(v1[2], v1[3]);
;                     __builtin_nontemporal_store(w, (u32x4*)rowp);
;                 }
.Lepi_nb_b:
	v_pk_mul_f32 v[118:119], v[108:109], v[108:109]
	v_and_b32_e32 v120, 0x7fffffff, v110
	v_and_b32_e32 v115, 0x7fffffff, v109
	v_and_b32_e32 v114, 0x7fffffff, v108
	v_pk_fma_f32 v[114:115], v[114:115], s[28:29], 1.0 op_sel_hi:[1,0,0]
	v_pk_mul_f32 v[118:119], v[118:119], s[74:75] op_sel_hi:[1,0]
	v_rcp_f32_e32 v114, v114
	v_rcp_f32_e32 v115, v115
	v_exp_f32_e32 v118, v118
	v_exp_f32_e32 v119, v119
	v_pk_fma_f32 v[120:121], v[120:121], s[28:29], 1.0 op_sel_hi:[1,0,0]
	v_pk_fma_f32 v[116:117], v[114:115], s[30:31], v[150:151] op_sel_hi:[1,0,0]
	v_rcp_f32_e32 v120, v120
	v_pk_fma_f32 v[116:117], v[114:115], v[116:117], s[36:37] op_sel_hi:[1,1,0]
	v_rcp_f32_e32 v121, v121
	v_pk_fma_f32 v[116:117], v[114:115], v[116:117], s[50:51] op_sel_hi:[1,1,0]
	v_or_b32_e32 v112, 16, v146
	v_pk_fma_f32 v[116:117], v[114:115], v[116:117], s[72:73] op_sel_hi:[1,1,0]
	v_ashrrev_i32_e32 v113, 31, v112
	v_pk_mul_f32 v[114:115], v[114:115], v[116:117]
	v_pk_mul_f32 v[116:117], v[110:111], v[110:111]
	v_pk_mul_f32 v[114:115], v[118:119], v[114:115]
	v_pk_mul_f32 v[116:117], v[116:117], s[74:75] op_sel_hi:[1,0]
	v_pk_mul_f32 v[118:119], v[108:109], v[114:115]
	v_pk_fma_f32 v[114:115], v[108:109], v[114:115], v[108:109] neg_lo:[1,0,0] neg_hi:[1,0,0]
	v_exp_f32_e32 v116, v116
	v_cndmask_b32_e32 v108, v114, v118, vcc
	v_cmp_gt_f32_e32 vcc, 0, v109
	v_exp_f32_e32 v117, v117
	v_lshlrev_b64 v[112:113], 11, v[112:113]
	v_cndmask_b32_e32 v109, v115, v119, vcc
	v_pk_fma_f32 v[114:115], v[120:121], s[30:31], v[150:151] op_sel_hi:[1,0,0]
	v_cmp_gt_f32_e32 vcc, 0, v110
	v_pk_fma_f32 v[114:115], v[120:121], v[114:115], s[36:37] op_sel_hi:[1,1,0]
	v_lshl_add_u64 v[112:113], v[152:153], 0, v[112:113]
	v_pk_fma_f32 v[114:115], v[120:121], v[114:115], s[50:51] op_sel_hi:[1,1,0]
	s_mov_b32 s6, 0x40000
	v_pk_fma_f32 v[114:115], v[120:121], v[114:115], s[72:73] op_sel_hi:[1,1,0]
	s_nop 0
	v_pk_mul_f32 v[114:115], v[120:121], v[114:115]
	s_nop 0
	v_pk_mul_f32 v[114:115], v[116:117], v[114:115]
	s_nop 0
	v_pk_mul_f32 v[116:117], v[110:111], v[114:115]
	v_pk_fma_f32 v[114:115], v[110:111], v[114:115], v[110:111] neg_lo:[1,0,0] neg_hi:[1,0,0]
	s_nop 0
	v_cndmask_b32_e32 v110, v114, v116, vcc
	v_mul_f32_e32 v116, 0xbfb8aa3b, v105
	v_mul_f32_e32 v114, 0xbfb8aa3b, v104
	v_exp_f32_e32 v116, v116
	v_exp_f32_e32 v114, v114
	v_cmp_gt_f32_e32 vcc, 0, v111
	v_add_f32_e32 v114, 1.0, v114
	s_nop 0
	v_cndmask_b32_e32 v111, v115, v117, vcc
	v_add_f32_e32 v115, 1.0, v116
	v_mul_f32_e32 v116, 0xbfb8aa3b, v106
	v_mul_f32_e32 v117, 0xbfb8aa3b, v107
	v_exp_f32_e32 v116, v116
	v_exp_f32_e32 v117, v117
	v_rcp_f32_e32 v114, v114
	v_rcp_f32_e32 v115, v115
	v_add_f32_e32 v116, 1.0, v116
	v_add_f32_e32 v117, 1.0, v117
	v_rcp_f32_e32 v116, v116
	v_rcp_f32_e32 v117, v117
	v_pk_mul_f32 v[104:105], v[104:105], v[114:115]
	v_and_b32_e32 v115, 0x7fffffff, v101
	v_and_b32_e32 v114, 0x7fffffff, v100
	v_pk_fma_f32 v[114:115], v[114:115], s[28:29], 1.0 op_sel_hi:[1,0,0]
	v_pk_mul_f32 v[106:107], v[106:107], v[116:117]
	v_rcp_f32_e32 v114, v114
	v_rcp_f32_e32 v115, v115
	v_pk_mul_f32 v[106:107], v[110:111], v[106:107]
	v_pk_mul_f32 v[110:111], v[100:101], v[100:101]
	v_pk_mul_f32 v[104:105], v[108:109], v[104:105]
	v_pk_fma_f32 v[108:109], v[114:115], s[30:31], v[150:151] op_sel_hi:[1,0,0]
	v_pk_mul_f32 v[110:111], v[110:111], s[74:75] op_sel_hi:[1,0]
	v_pk_fma_f32 v[108:109], v[114:115], v[108:109], s[36:37] op_sel_hi:[1,1,0]
	v_exp_f32_e32 v110, v110
	v_exp_f32_e32 v111, v111
	v_pk_fma_f32 v[108:109], v[114:115], v[108:109], s[50:51] op_sel_hi:[1,1,0]
	v_and_b32_e32 v117, 0x7fffffff, v103
	v_and_b32_e32 v116, 0x7fffffff, v102
	v_pk_fma_f32 v[108:109], v[114:115], v[108:109], s[72:73] op_sel_hi:[1,1,0]
	v_pk_fma_f32 v[116:117], v[116:117], s[28:29], 1.0 op_sel_hi:[1,0,0]
	v_pk_mul_f32 v[108:109], v[114:115], v[108:109]
	v_rcp_f32_e32 v116, v116
	v_rcp_f32_e32 v117, v117
	v_pk_mul_f32 v[108:109], v[110:111], v[108:109]
	v_cmp_gt_f32_e32 vcc, 0, v100
	v_pk_mul_f32 v[110:111], v[100:101], v[108:109]
	v_pk_fma_f32 v[108:109], v[100:101], v[108:109], v[100:101] neg_lo:[1,0,0] neg_hi:[1,0,0]
	v_pk_mul_f32 v[114:115], v[102:103], v[102:103]
	v_cndmask_b32_e32 v100, v108, v110, vcc
	v_cmp_gt_f32_e32 vcc, 0, v101
	s_nop 1
	v_cndmask_b32_e32 v101, v109, v111, vcc
	v_pk_fma_f32 v[108:109], v[116:117], s[30:31], v[150:151] op_sel_hi:[1,0,0]
	v_pk_mul_f32 v[110:111], v[114:115], s[74:75] op_sel_hi:[1,0]
	v_pk_fma_f32 v[108:109], v[116:117], v[108:109], s[36:37] op_sel_hi:[1,1,0]
	v_exp_f32_e32 v110, v110
	v_exp_f32_e32 v111, v111
	v_pk_fma_f32 v[108:109], v[116:117], v[108:109], s[50:51] op_sel_hi:[1,1,0]
	v_mul_f32_e32 v114, 0xbfb8aa3b, v96
	v_pk_fma_f32 v[108:109], v[116:117], v[108:109], s[72:73] op_sel_hi:[1,1,0]
	v_exp_f32_e32 v114, v114
	v_mul_f32_e32 v115, 0xbfb8aa3b, v97
	v_pk_mul_f32 v[108:109], v[116:117], v[108:109]
	v_exp_f32_e32 v115, v115
	v_pk_mul_f32 v[108:109], v[110:111], v[108:109]
	v_cmp_gt_f32_e32 vcc, 0, v102
	v_pk_mul_f32 v[110:111], v[102:103], v[108:109]
	v_pk_fma_f32 v[108:109], v[102:103], v[108:109], v[102:103] neg_lo:[1,0,0] neg_hi:[1,0,0]
	s_nop 0
	v_cndmask_b32_e32 v102, v108, v110, vcc
	v_add_f32_e32 v108, 1.0, v114
	v_mul_f32_e32 v110, 0xbfb8aa3b, v98
	v_rcp_f32_e32 v114, v108
	v_add_f32_e32 v108, 1.0, v115
	v_exp_f32_e32 v110, v110
	v_mul_f32_e32 v115, 0xbfb8aa3b, v99
	v_exp_f32_e32 v117, v115
	v_rcp_f32_e32 v115, v108
	v_add_f32_e32 v108, 1.0, v110
	v_rcp_f32_e32 v116, v108
	v_add_f32_e32 v108, 1.0, v117
	v_rcp_f32_e32 v117, v108
	v_cmp_gt_f32_e32 vcc, 0, v103
	v_pk_mul_f32 v[96:97], v[96:97], v[114:115]
	v_pk_mul_f32 v[98:99], v[98:99], v[116:117]
	v_cndmask_b32_e32 v103, v109, v111, vcc
; __device__ __forceinline__ unsigned cvt_pk_bf16(float lo, float hi) { unsigned r; asm volatile("v_cvt_pk_bf16_f32 %0, %1, %2" : "=v"(r) : "v"(lo), "v"(hi)); return r; }
; __device__ __forceinline__ float sigmoid_f(float x) { return __builtin_amdgcn_rcpf(1.0f + __builtin_amdgcn_exp2f(-1.44269504f * x)); }
; __device__ __forceinline__ f32x2 gelu_pk(f32x2 v) {
;     const f32x2 av = __builtin_elementwise_abs(v), d = av * 0.2316418882f + 1.0f;
;     f32x2 t; t.x = __builtin_amdgcn_rcpf(d.x); t.y = __builtin_amdgcn_rcpf(d.y);
;     f32x2 q = t * 0.5307027145f + (-0.7265760135f); q = q * t + 0.7107068705f; q = q * t + (-0.142248368f); q = q * t + 0.127414796f; q = q * t;
;     const f32x2 s = (v * v) * (-0.72134752044f);
;     f32x2 e; e.x = __builtin_amdgcn_exp2f(s.x); e.y = __builtin_amdgcn_exp2f(s.y);
;     const f32x2 m = v * (q * e), r = v - m;
;     f32x2 o; o.x = v.x < 0.f ? m.x : r.x; o.y = v.y < 0.f ? m.y : r.y; return o;
; }
; __device__ __forceinline__ f32x4 gelu4(f32x4 v) { f32x2 a = gelu_pk((f32x2){v[0], v[1]}), b = gelu_pk((f32x2){v[2], v[3]}); return (f32x4){a.x, a.y, b.x, b.y}; }
; __device__ __forceinline__ f32x4 sigm4(f32x4 v) { return (f32x4){sigmoid_f(v[0]), sigmoid_f(v[1]), sigmoid_f(v[2]), sigmoid_f(v[3])}; }
; __device__ __forceinline__ f32x4 silu4(f32x4 v) { return v * sigm4(v); }
;     __device__ __forceinline__ void operator()(const f32x4 (&acc)[2][2][4][2], const pg8::Unit& u, int wr, int wc, int fr, int fq) const {
;     ...
;         if (pn < 8) {
;             bf16_t* base = PJ + T_P + 128 * pn + wc * 32 + 8 * fq;
; #pragma unroll
;             for (int ai = 0; ai < 2; ++ai)
; #pragma unroll
;                 for (int m = 0; m < 4; ++m) {
;                     bf16_t* rowp = base + (size_t)(row0 + ai * 128 + m * 16) * 1024;
;                     const f32x4 v0 = gelu4(acc[ai][0][m][0]) * silu4(acc[ai][1][m][0]), v1 = gelu4(acc[ai][0][m][1]) * silu4(acc[ai][1][m][1]);
;                     u32x4 w; w.x = cvt_pk_bf16(v0[0], v0[1]); w.y = cvt_pk_bf16(v0[2], v0[3]); w.z = cvt_pk_bf16(v1[0], v1[1]); w.w = cvt_pk_bf16(v1[2], v1[3]);
;                     __builtin_nontemporal_store(w, (u32x4*)rowp);
;                 }
	v_pk_mul_f32 v[102:103], v[102:103], v[98:99]
	v_pk_mul_f32 v[98:99], v[100:101], v[96:97]
	v_cvt_pk_bf16_f32 v96, v104, v105
	v_cvt_pk_bf16_f32 v97, v106, v107
	v_and_b32_e32 v105, 0x7fffffff, v95
	v_cvt_pk_bf16_f32 v98, v98, v99
	v_cvt_pk_bf16_f32 v99, v102, v103
	global_store_dwordx4 v[112:113], v[96:99], off nt
	v_pk_mul_f32 v[102:103], v[92:93], v[92:93]
	v_and_b32_e32 v104, 0x7fffffff, v94
	v_and_b32_e32 v99, 0x7fffffff, v93
	v_and_b32_e32 v98, 0x7fffffff, v92
	v_pk_fma_f32 v[98:99], v[98:99], s[28:29], 1.0 op_sel_hi:[1,0,0]
	v_pk_mul_f32 v[102:103], v[102:103], s[74:75] op_sel_hi:[1,0]
	v_rcp_f32_e32 v98, v98
	v_rcp_f32_e32 v99, v99
	v_exp_f32_e32 v102, v102
	v_exp_f32_e32 v103, v103
	v_pk_fma_f32 v[104:105], v[104:105], s[28:29], 1.0 op_sel_hi:[1,0,0]
	v_pk_fma_f32 v[100:101], v[98:99], s[30:31], v[150:151] op_sel_hi:[1,0,0]
	v_rcp_f32_e32 v104, v104
	v_pk_fma_f32 v[100:101], v[98:99], v[100:101], s[36:37] op_sel_hi:[1,1,0]
	v_rcp_f32_e32 v105, v105
	v_pk_fma_f32 v[100:101], v[98:99], v[100:101], s[50:51] op_sel_hi:[1,1,0]
	v_cmp_gt_f32_e32 vcc, 0, v92
	v_pk_fma_f32 v[100:101], v[98:99], v[100:101], s[72:73] op_sel_hi:[1,1,0]
	v_or_b32_e32 v96, 32, v146
	v_pk_mul_f32 v[98:99], v[98:99], v[100:101]
	v_pk_mul_f32 v[100:101], v[94:95], v[94:95]
	v_pk_mul_f32 v[98:99], v[102:103], v[98:99]
	v_pk_mul_f32 v[100:101], v[100:101], s[74:75] op_sel_hi:[1,0]
	v_pk_mul_f32 v[102:103], v[92:93], v[98:99]
	v_pk_fma_f32 v[98:99], v[92:93], v[98:99], v[92:93] neg_lo:[1,0,0] neg_hi:[1,0,0]
	v_exp_f32_e32 v100, v100
	v_cndmask_b32_e32 v92, v98, v102, vcc
	v_cmp_gt_f32_e32 vcc, 0, v93
	v_exp_f32_e32 v101, v101
	v_ashrrev_i32_e32 v97, 31, v96
	v_cndmask_b32_e32 v93, v99, v103, vcc
	v_pk_fma_f32 v[98:99], v[104:105], s[30:31], v[150:151] op_sel_hi:[1,0,0]
	v_cmp_gt_f32_e32 vcc, 0, v94
	v_pk_fma_f32 v[98:99], v[104:105], v[98:99], s[36:37] op_sel_hi:[1,1,0]
	v_lshlrev_b64 v[96:97], 11, v[96:97]
	v_pk_fma_f32 v[98:99], v[104:105], v[98:99], s[50:51] op_sel_hi:[1,1,0]
	v_lshl_add_u64 v[96:97], v[152:153], 0, v[96:97]
	v_pk_fma_f32 v[98:99], v[104:105], v[98:99], s[72:73] op_sel_hi:[1,1,0]
	s_nop 0
	v_pk_mul_f32 v[98:99], v[104:105], v[98:99]
	s_nop 0
	v_pk_mul_f32 v[98:99], v[100:101], v[98:99]
	s_nop 0
	v_pk_mul_f32 v[100:101], v[94:95], v[98:99]
	v_pk_fma_f32 v[98:99], v[94:95], v[98:99], v[94:95] neg_lo:[1,0,0] neg_hi:[1,0,0]
	s_nop 0
	v_cndmask_b32_e32 v94, v98, v100, vcc
	v_mul_f32_e32 v100, 0xbfb8aa3b, v89
	v_mul_f32_e32 v98, 0xbfb8aa3b, v88
	v_exp_f32_e32 v100, v100
	v_exp_f32_e32 v98, v98
	v_cmp_gt_f32_e32 vcc, 0, v95
	v_add_f32_e32 v98, 1.0, v98
	s_nop 0
	v_cndmask_b32_e32 v95, v99, v101, vcc
	v_add_f32_e32 v99, 1.0, v100
	v_mul_f32_e32 v100, 0xbfb8aa3b, v90
	v_mul_f32_e32 v101, 0xbfb8aa3b, v91
	v_exp_f32_e32 v100, v100
	v_exp_f32_e32 v101, v101
	v_rcp_f32_e32 v98, v98
	v_rcp_f32_e32 v99, v99
	v_add_f32_e32 v100, 1.0, v100
	v_add_f32_e32 v101, 1.0, v101
	v_rcp_f32_e32 v100, v100
	v_rcp_f32_e32 v101, v101
	v_pk_mul_f32 v[88:89], v[88:89], v[98:99]
	v_and_b32_e32 v99, 0x7fffffff, v85
	v_and_b32_e32 v98, 0x7fffffff, v84
	v_pk_fma_f32 v[98:99], v[98:99], s[28:29], 1.0 op_sel_hi:[1,0,0]
	v_pk_mul_f32 v[90:91], v[90:91], v[100:101]
	v_rcp_f32_e32 v98, v98
	v_rcp_f32_e32 v99, v99
	v_pk_mul_f32 v[90:91], v[94:95], v[90:91]
	v_pk_mul_f32 v[94:95], v[84:85], v[84:85]
	v_pk_mul_f32 v[88:89], v[92:93], v[88:89]
	v_pk_fma_f32 v[92:93], v[98:99], s[30:31], v[150:151] op_sel_hi:[1,0,0]
	v_pk_mul_f32 v[94:95], v[94:95], s[74:75] op_sel_hi:[1,0]
	v_pk_fma_f32 v[92:93], v[98:99], v[92:93], s[36:37] op_sel_hi:[1,1,0]
	v_exp_f32_e32 v94, v94
	v_exp_f32_e32 v95, v95
	v_pk_fma_f32 v[92:93], v[98:99], v[92:93], s[50:51] op_sel_hi:[1,1,0]
	v_and_b32_e32 v101, 0x7fffffff, v87
	v_and_b32_e32 v100, 0x7fffffff, v86
	v_pk_fma_f32 v[92:93], v[98:99], v[92:93], s[72:73] op_sel_hi:[1,1,0]
	v_pk_fma_f32 v[100:101], v[100:101], s[28:29], 1.0 op_sel_hi:[1,0,0]
	v_pk_mul_f32 v[92:93], v[98:99], v[92:93]
	v_rcp_f32_e32 v100, v100
	v_rcp_f32_e32 v101, v101
	v_pk_mul_f32 v[92:93], v[94:95], v[92:93]
	v_cmp_gt_f32_e32 vcc, 0, v84
	v_pk_mul_f32 v[94:95], v[84:85], v[92:93]
	v_pk_fma_f32 v[92:93], v[84:85], v[92:93], v[84:85] neg_lo:[1,0,0] neg_hi:[1,0,0]
	v_pk_mul_f32 v[98:99], v[86:87], v[86:87]
	v_cndmask_b32_e32 v84, v92, v94, vcc
	v_cmp_gt_f32_e32 vcc, 0, v85
	s_nop 1
	v_cndmask_b32_e32 v85, v93, v95, vcc
	v_pk_fma_f32 v[92:93], v[100:101], s[30:31], v[150:151] op_sel_hi:[1,0,0]
	v_pk_mul_f32 v[94:95], v[98:99], s[74:75] op_sel_hi:[1,0]
	v_pk_fma_f32 v[92:93], v[100:101], v[92:93], s[36:37] op_sel_hi:[1,1,0]
	v_exp_f32_e32 v94, v94
	v_exp_f32_e32 v95, v95
	v_pk_fma_f32 v[92:93], v[100:101], v[92:93], s[50:51] op_sel_hi:[1,1,0]
	v_mul_f32_e32 v98, 0xbfb8aa3b, v80
	v_pk_fma_f32 v[92:93], v[100:101], v[92:93], s[72:73] op_sel_hi:[1,1,0]
	v_exp_f32_e32 v98, v98
	v_mul_f32_e32 v99, 0xbfb8aa3b, v81
	v_pk_mul_f32 v[92:93], v[100:101], v[92:93]
	v_exp_f32_e32 v99, v99
	v_pk_mul_f32 v[92:93], v[94:95], v[92:93]
	v_cmp_gt_f32_e32 vcc, 0, v86
	v_pk_mul_f32 v[94:95], v[86:87], v[92:93]
	v_pk_fma_f32 v[92:93], v[86:87], v[92:93], v[86:87] neg_lo:[1,0,0] neg_hi:[1,0,0]
	s_nop 0
	v_cndmask_b32_e32 v86, v92, v94, vcc
	v_add_f32_e32 v92, 1.0, v98
	v_mul_f32_e32 v94, 0xbfb8aa3b, v82
	v_rcp_f32_e32 v98, v92
	v_add_f32_e32 v92, 1.0, v99
	v_exp_f32_e32 v94, v94
	v_mul_f32_e32 v99, 0xbfb8aa3b, v83
	v_exp_f32_e32 v101, v99
	v_rcp_f32_e32 v99, v92
	v_add_f32_e32 v92, 1.0, v94
	v_rcp_f32_e32 v100, v92
	v_add_f32_e32 v92, 1.0, v101
	v_rcp_f32_e32 v101, v92
	v_cmp_gt_f32_e32 vcc, 0, v87
	v_pk_mul_f32 v[80:81], v[80:81], v[98:99]
	v_pk_mul_f32 v[82:83], v[82:83], v[100:101]
	v_cndmask_b32_e32 v87, v93, v95, vcc
; __device__ __forceinline__ unsigned cvt_pk_bf16(float lo, float hi) { unsigned r; asm volatile("v_cvt_pk_bf16_f32 %0, %1, %2" : "=v"(r) : "v"(lo), "v"(hi)); return r; }
; __device__ __forceinline__ float sigmoid_f(float x) { return __builtin_amdgcn_rcpf(1.0f + __builtin_amdgcn_exp2f(-1.44269504f * x)); }
; __device__ __forceinline__ f32x2 gelu_pk(f32x2 v) {
;     const f32x2 av = __builtin_elementwise_abs(v), d = av * 0.2316418882f + 1.0f;
;     f32x2 t; t.x = __builtin_amdgcn_rcpf(d.x); t.y = __builtin_amdgcn_rcpf(d.y);
;     f32x2 q = t * 0.5307027145f + (-0.7265760135f); q = q * t + 0.7107068705f; q = q * t + (-0.142248368f); q = q * t + 0.127414796f; q = q * t;
;     const f32x2 s = (v * v) * (-0.72134752044f);
;     f32x2 e; e.x = __builtin_amdgcn_exp2f(s.x); e.y = __builtin_amdgcn_exp2f(s.y);
;     const f32x2 m = v * (q * e), r = v - m;
;     f32x2 o; o.x = v.x < 0.f ? m.x : r.x; o.y = v.y < 0.f ? m.y : r.y; return o;
; }
; __device__ __forceinline__ f32x4 gelu4(f32x4 v) { f32x2 a = gelu_pk((f32x2){v[0], v[1]}), b = gelu_pk((f32x2){v[2], v[3]}); return (f32x4){a.x, a.y, b.x, b.y}; }
; __device__ __forceinline__ f32x4 sigm4(f32x4 v) { return (f32x4){sigmoid_f(v[0]), sigmoid_f(v[1]), sigmoid_f(v[2]), sigmoid_f(v[3])}; }
; __device__ __forceinline__ f32x4 silu4(f32x4 v) { return v * sigm4(v); }
;     __device__ __forceinline__ void operator()(const f32x4 (&acc)[2][2][4][2], const pg8::Unit& u, int wr, int wc, int fr, int fq) const {
;     ...
;         if (pn < 8) {
;             bf16_t* base = PJ + T_P + 128 * pn + wc * 32 + 8 * fq;
; #pragma unroll
;             for (int ai = 0; ai < 2; ++ai)
; #pragma unroll
;                 for (int m = 0; m < 4; ++m) {
;                     bf16_t* rowp = base + (size_t)(row0 + ai * 128 + m * 16) * 1024;
;                     const f32x4 v0 = gelu4(acc[ai][0][m][0]) * silu4(acc[ai][1][m][0]), v1 = gelu4(acc[ai][0][m][1]) * silu4(acc[ai][1][m][1]);
;                     u32x4 w; w.x = cvt_pk_bf16(v0[0], v0[1]); w.y = cvt_pk_bf16(v0[2], v0[3]); w.z = cvt_pk_bf16(v1[0], v1[1]); w.w = cvt_pk_bf16(v1[2], v1[3]);
;                     __builtin_nontemporal_store(w, (u32x4*)rowp);
;                 }
	v_pk_mul_f32 v[86:87], v[86:87], v[82:83]
	v_pk_mul_f32 v[82:83], v[84:85], v[80:81]
	v_cvt_pk_bf16_f32 v80, v88, v89
	v_cvt_pk_bf16_f32 v81, v90, v91
	v_and_b32_e32 v89, 0x7fffffff, v79
	v_cvt_pk_bf16_f32 v82, v82, v83
	v_cvt_pk_bf16_f32 v83, v86, v87
	global_store_dwordx4 v[96:97], v[80:83], off nt
	v_pk_mul_f32 v[86:87], v[76:77], v[76:77]
	v_and_b32_e32 v88, 0x7fffffff, v78
	v_and_b32_e32 v83, 0x7fffffff, v77
	v_and_b32_e32 v82, 0x7fffffff, v76
	v_pk_fma_f32 v[82:83], v[82:83], s[28:29], 1.0 op_sel_hi:[1,0,0]
	v_pk_mul_f32 v[86:87], v[86:87], s[74:75] op_sel_hi:[1,0]
	v_rcp_f32_e32 v82, v82
	v_rcp_f32_e32 v83, v83
	v_exp_f32_e32 v86, v86
	v_exp_f32_e32 v87, v87
	v_pk_fma_f32 v[88:89], v[88:89], s[28:29], 1.0 op_sel_hi:[1,0,0]
	v_pk_fma_f32 v[84:85], v[82:83], s[30:31], v[150:151] op_sel_hi:[1,0,0]
	v_rcp_f32_e32 v88, v88
	v_pk_fma_f32 v[84:85], v[82:83], v[84:85], s[36:37] op_sel_hi:[1,1,0]
	v_rcp_f32_e32 v89, v89
	v_pk_fma_f32 v[84:85], v[82:83], v[84:85], s[50:51] op_sel_hi:[1,1,0]
	v_cmp_gt_f32_e32 vcc, 0, v76
	v_pk_fma_f32 v[84:85], v[82:83], v[84:85], s[72:73] op_sel_hi:[1,1,0]
	v_or_b32_e32 v80, 48, v146
	v_pk_mul_f32 v[82:83], v[82:83], v[84:85]
	v_pk_mul_f32 v[84:85], v[78:79], v[78:79]
	v_pk_mul_f32 v[82:83], v[86:87], v[82:83]
	v_pk_mul_f32 v[84:85], v[84:85], s[74:75] op_sel_hi:[1,0]
	v_pk_mul_f32 v[86:87], v[76:77], v[82:83]
	v_pk_fma_f32 v[82:83], v[76:77], v[82:83], v[76:77] neg_lo:[1,0,0] neg_hi:[1,0,0]
	v_exp_f32_e32 v84, v84
	v_cndmask_b32_e32 v76, v82, v86, vcc
	v_cmp_gt_f32_e32 vcc, 0, v77
	v_exp_f32_e32 v85, v85
	v_ashrrev_i32_e32 v81, 31, v80
	v_cndmask_b32_e32 v77, v83, v87, vcc
	v_pk_fma_f32 v[82:83], v[88:89], s[30:31], v[150:151] op_sel_hi:[1,0,0]
	v_cmp_gt_f32_e32 vcc, 0, v78
	v_pk_fma_f32 v[82:83], v[88:89], v[82:83], s[36:37] op_sel_hi:[1,1,0]
	v_lshlrev_b64 v[80:81], 11, v[80:81]
	v_pk_fma_f32 v[82:83], v[88:89], v[82:83], s[50:51] op_sel_hi:[1,1,0]
	v_lshl_add_u64 v[80:81], v[152:153], 0, v[80:81]
	v_pk_fma_f32 v[82:83], v[88:89], v[82:83], s[72:73] op_sel_hi:[1,1,0]
	s_nop 0
	v_pk_mul_f32 v[82:83], v[88:89], v[82:83]
	s_nop 0
	v_pk_mul_f32 v[82:83], v[84:85], v[82:83]
	s_nop 0
	v_pk_mul_f32 v[84:85], v[78:79], v[82:83]
	v_pk_fma_f32 v[82:83], v[78:79], v[82:83], v[78:79] neg_lo:[1,0,0] neg_hi:[1,0,0]
	s_nop 0
	v_cndmask_b32_e32 v78, v82, v84, vcc
	v_mul_f32_e32 v84, 0xbfb8aa3b, v73
	v_mul_f32_e32 v82, 0xbfb8aa3b, v72
	v_exp_f32_e32 v84, v84
	v_exp_f32_e32 v82, v82
	v_cmp_gt_f32_e32 vcc, 0, v79
	v_add_f32_e32 v82, 1.0, v82
	s_nop 0
	v_cndmask_b32_e32 v79, v83, v85, vcc
	v_add_f32_e32 v83, 1.0, v84
	v_mul_f32_e32 v84, 0xbfb8aa3b, v74
	v_mul_f32_e32 v85, 0xbfb8aa3b, v75
	v_exp_f32_e32 v84, v84
	v_exp_f32_e32 v85, v85
	v_rcp_f32_e32 v82, v82
	v_rcp_f32_e32 v83, v83
	v_add_f32_e32 v84, 1.0, v84
	v_add_f32_e32 v85, 1.0, v85
	v_rcp_f32_e32 v84, v84
	v_rcp_f32_e32 v85, v85
	v_pk_mul_f32 v[72:73], v[72:73], v[82:83]
	v_and_b32_e32 v83, 0x7fffffff, v69
	v_and_b32_e32 v82, 0x7fffffff, v68
	v_pk_fma_f32 v[82:83], v[82:83], s[28:29], 1.0 op_sel_hi:[1,0,0]
	v_pk_mul_f32 v[74:75], v[74:75], v[84:85]
	v_rcp_f32_e32 v82, v82
	v_rcp_f32_e32 v83, v83
	v_pk_mul_f32 v[74:75], v[78:79], v[74:75]
	v_pk_mul_f32 v[78:79], v[68:69], v[68:69]
	v_pk_mul_f32 v[72:73], v[76:77], v[72:73]
	v_pk_fma_f32 v[76:77], v[82:83], s[30:31], v[150:151] op_sel_hi:[1,0,0]
	v_pk_mul_f32 v[78:79], v[78:79], s[74:75] op_sel_hi:[1,0]
	v_pk_fma_f32 v[76:77], v[82:83], v[76:77], s[36:37] op_sel_hi:[1,1,0]
	v_exp_f32_e32 v78, v78
	v_exp_f32_e32 v79, v79
	v_pk_fma_f32 v[76:77], v[82:83], v[76:77], s[50:51] op_sel_hi:[1,1,0]
	v_and_b32_e32 v85, 0x7fffffff, v71
	v_and_b32_e32 v84, 0x7fffffff, v70
	v_pk_fma_f32 v[76:77], v[82:83], v[76:77], s[72:73] op_sel_hi:[1,1,0]
	v_pk_fma_f32 v[84:85], v[84:85], s[28:29], 1.0 op_sel_hi:[1,0,0]
	v_pk_mul_f32 v[76:77], v[82:83], v[76:77]
	v_rcp_f32_e32 v84, v84
	v_rcp_f32_e32 v85, v85
	v_pk_mul_f32 v[76:77], v[78:79], v[76:77]
	v_cmp_gt_f32_e32 vcc, 0, v68
	v_pk_mul_f32 v[78:79], v[68:69], v[76:77]
	v_pk_fma_f32 v[76:77], v[68:69], v[76:77], v[68:69] neg_lo:[1,0,0] neg_hi:[1,0,0]
	v_pk_mul_f32 v[82:83], v[70:71], v[70:71]
	v_cndmask_b32_e32 v68, v76, v78, vcc
	v_cmp_gt_f32_e32 vcc, 0, v69
	s_nop 1
	v_cndmask_b32_e32 v69, v77, v79, vcc
	v_pk_fma_f32 v[76:77], v[84:85], s[30:31], v[150:151] op_sel_hi:[1,0,0]
	v_pk_mul_f32 v[78:79], v[82:83], s[74:75] op_sel_hi:[1,0]
	v_pk_fma_f32 v[76:77], v[84:85], v[76:77], s[36:37] op_sel_hi:[1,1,0]
	v_exp_f32_e32 v78, v78
	v_exp_f32_e32 v79, v79
	v_pk_fma_f32 v[76:77], v[84:85], v[76:77], s[50:51] op_sel_hi:[1,1,0]
	v_mul_f32_e32 v82, 0xbfb8aa3b, v64
	v_pk_fma_f32 v[76:77], v[84:85], v[76:77], s[72:73] op_sel_hi:[1,1,0]
	v_exp_f32_e32 v82, v82
	v_mul_f32_e32 v83, 0xbfb8aa3b, v65
	v_pk_mul_f32 v[76:77], v[84:85], v[76:77]
	v_exp_f32_e32 v83, v83
	v_pk_mul_f32 v[76:77], v[78:79], v[76:77]
	v_cmp_gt_f32_e32 vcc, 0, v70
	v_pk_mul_f32 v[78:79], v[70:71], v[76:77]
	v_pk_fma_f32 v[76:77], v[70:71], v[76:77], v[70:71] neg_lo:[1,0,0] neg_hi:[1,0,0]
	s_nop 0
	v_cndmask_b32_e32 v70, v76, v78, vcc
	v_add_f32_e32 v76, 1.0, v82
	v_mul_f32_e32 v78, 0xbfb8aa3b, v66
	v_rcp_f32_e32 v82, v76
	v_add_f32_e32 v76, 1.0, v83
	v_exp_f32_e32 v78, v78
	v_mul_f32_e32 v83, 0xbfb8aa3b, v67
	v_exp_f32_e32 v85, v83
	v_rcp_f32_e32 v83, v76
	v_add_f32_e32 v76, 1.0, v78
	v_rcp_f32_e32 v84, v76
	v_add_f32_e32 v76, 1.0, v85
	v_rcp_f32_e32 v85, v76
	v_cmp_gt_f32_e32 vcc, 0, v71
	v_pk_mul_f32 v[64:65], v[64:65], v[82:83]
	v_pk_mul_f32 v[66:67], v[66:67], v[84:85]
	v_cndmask_b32_e32 v71, v77, v79, vcc
	v_pk_mul_f32 v[70:71], v[70:71], v[66:67]
	v_pk_mul_f32 v[66:67], v[68:69], v[64:65]
	v_and_b32_e32 v69, 0x7fffffff, v61
; __device__ __forceinline__ unsigned cvt_pk_bf16(float lo, float hi) { unsigned r; asm volatile("v_cvt_pk_bf16_f32 %0, %1, %2" : "=v"(r) : "v"(lo), "v"(hi)); return r; }
; __device__ __forceinline__ float sigmoid_f(float x) { return __builtin_amdgcn_rcpf(1.0f + __builtin_amdgcn_exp2f(-1.44269504f * x)); }
; __device__ __forceinline__ f32x2 gelu_pk(f32x2 v) {
;     const f32x2 av = __builtin_elementwise_abs(v), d = av * 0.2316418882f + 1.0f;
;     f32x2 t; t.x = __builtin_amdgcn_rcpf(d.x); t.y = __builtin_amdgcn_rcpf(d.y);
;     f32x2 q = t * 0.5307027145f + (-0.7265760135f); q = q * t + 0.7107068705f; q = q * t + (-0.142248368f); q = q * t + 0.127414796f; q = q * t;
;     const f32x2 s = (v * v) * (-0.72134752044f);
;     f32x2 e; e.x = __builtin_amdgcn_exp2f(s.x); e.y = __builtin_amdgcn_exp2f(s.y);
;     const f32x2 m = v * (q * e), r = v - m;
;     f32x2 o; o.x = v.x < 0.f ? m.x : r.x; o.y = v.y < 0.f ? m.y : r.y; return o;
; }
; __device__ __forceinline__ f32x4 gelu4(f32x4 v) { f32x2 a = gelu_pk((f32x2){v[0], v[1]}), b = gelu_pk((f32x2){v[2], v[3]}); return (f32x4){a.x, a.y, b.x, b.y}; }
; __device__ __forceinline__ f32x4 sigm4(f32x4 v) { return (f32x4){sigmoid_f(v[0]), sigmoid_f(v[1]), sigmoid_f(v[2]), sigmoid_f(v[3])}; }
; __device__ __forceinline__ f32x4 silu4(f32x4 v) { return v * sigm4(v); }
;     __device__ __forceinline__ void operator()(const f32x4 (&acc)[2][2][4][2], const pg8::Unit& u, int wr, int wc, int fr, int fq) const {
;     ...
;         if (pn < 8) {
;             bf16_t* base = PJ + T_P + 128 * pn + wc * 32 + 8 * fq;
; #pragma unroll
;             for (int ai = 0; ai < 2; ++ai)
; #pragma unroll
;                 for (int m = 0; m < 4; ++m) {
;                     bf16_t* rowp = base + (size_t)(row0 + ai * 128 + m * 16) * 1024;
;                     const f32x4 v0 = gelu4(acc[ai][0][m][0]) * silu4(acc[ai][1][m][0]), v1 = gelu4(acc[ai][0][m][1]) * silu4(acc[ai][1][m][1]);
;                     u32x4 w; w.x = cvt_pk_bf16(v0[0], v0[1]); w.y = cvt_pk_bf16(v0[2], v0[3]); w.z = cvt_pk_bf16(v1[0], v1[1]); w.w = cvt_pk_bf16(v1[2], v1[3]);
;                     __builtin_nontemporal_store(w, (u32x4*)rowp);
;                 }
	v_and_b32_e32 v68, 0x7fffffff, v60
	v_pk_fma_f32 v[68:69], v[68:69], s[28:29], 1.0 op_sel_hi:[1,0,0]
	v_cvt_pk_bf16_f32 v64, v72, v73
	v_cvt_pk_bf16_f32 v65, v74, v75
	v_cvt_pk_bf16_f32 v66, v66, v67
	v_cvt_pk_bf16_f32 v67, v70, v71
	global_store_dwordx4 v[80:81], v[64:67], off nt
	v_rcp_f32_e32 v68, v68
	v_rcp_f32_e32 v69, v69
	v_pk_mul_f32 v[66:67], v[60:61], v[60:61]
	v_and_b32_e32 v71, 0x7fffffff, v63
	v_pk_mul_f32 v[66:67], v[66:67], s[74:75] op_sel_hi:[1,0]
	v_pk_fma_f32 v[64:65], v[68:69], s[30:31], v[150:151] op_sel_hi:[1,0,0]
	v_exp_f32_e32 v66, v66
	v_pk_fma_f32 v[64:65], v[68:69], v[64:65], s[36:37] op_sel_hi:[1,1,0]
	v_exp_f32_e32 v67, v67
	v_pk_fma_f32 v[64:65], v[68:69], v[64:65], s[50:51] op_sel_hi:[1,1,0]
	v_and_b32_e32 v70, 0x7fffffff, v62
	v_pk_fma_f32 v[64:65], v[68:69], v[64:65], s[72:73] op_sel_hi:[1,1,0]
	v_pk_fma_f32 v[70:71], v[70:71], s[28:29], 1.0 op_sel_hi:[1,0,0]
	v_pk_mul_f32 v[64:65], v[68:69], v[64:65]
	v_rcp_f32_e32 v70, v70
	v_rcp_f32_e32 v71, v71
	v_pk_mul_f32 v[64:65], v[66:67], v[64:65]
	v_cmp_gt_f32_e32 vcc, 0, v60
	v_pk_mul_f32 v[66:67], v[60:61], v[64:65]
	v_pk_fma_f32 v[64:65], v[60:61], v[64:65], v[60:61] neg_lo:[1,0,0] neg_hi:[1,0,0]
	v_pk_mul_f32 v[68:69], v[62:63], v[62:63]
	v_cndmask_b32_e32 v60, v64, v66, vcc
	v_cmp_gt_f32_e32 vcc, 0, v61
	s_nop 1
	v_cndmask_b32_e32 v61, v65, v67, vcc
	v_pk_fma_f32 v[64:65], v[70:71], s[30:31], v[150:151] op_sel_hi:[1,0,0]
	v_pk_mul_f32 v[66:67], v[68:69], s[74:75] op_sel_hi:[1,0]
	v_pk_fma_f32 v[64:65], v[70:71], v[64:65], s[36:37] op_sel_hi:[1,1,0]
	v_exp_f32_e32 v66, v66
	v_exp_f32_e32 v67, v67
	v_pk_fma_f32 v[64:65], v[70:71], v[64:65], s[50:51] op_sel_hi:[1,1,0]
	v_cmp_gt_f32_e32 vcc, 0, v62
	v_pk_fma_f32 v[64:65], v[70:71], v[64:65], s[72:73] op_sel_hi:[1,1,0]
	s_nop 0
	v_pk_mul_f32 v[64:65], v[70:71], v[64:65]
	s_nop 0
	v_pk_mul_f32 v[64:65], v[66:67], v[64:65]
	s_nop 0
	v_pk_mul_f32 v[66:67], v[62:63], v[64:65]
	v_pk_fma_f32 v[64:65], v[62:63], v[64:65], v[62:63] neg_lo:[1,0,0] neg_hi:[1,0,0]
	s_nop 0
	v_cndmask_b32_e32 v62, v64, v66, vcc
	v_mul_f32_e32 v66, 0xbfb8aa3b, v57
	v_mul_f32_e32 v64, 0xbfb8aa3b, v56
	v_exp_f32_e32 v66, v66
	v_exp_f32_e32 v64, v64
	v_cmp_gt_f32_e32 vcc, 0, v63
	v_add_f32_e32 v64, 1.0, v64
	s_nop 0
	v_cndmask_b32_e32 v63, v65, v67, vcc
	v_add_f32_e32 v65, 1.0, v66
	v_mul_f32_e32 v66, 0xbfb8aa3b, v58
	v_mul_f32_e32 v67, 0xbfb8aa3b, v59
	v_exp_f32_e32 v66, v66
	v_exp_f32_e32 v67, v67
	v_rcp_f32_e32 v64, v64
	v_rcp_f32_e32 v65, v65
	v_add_f32_e32 v66, 1.0, v66
	v_add_f32_e32 v67, 1.0, v67
	v_rcp_f32_e32 v66, v66
	v_rcp_f32_e32 v67, v67
	v_pk_mul_f32 v[56:57], v[56:57], v[64:65]
	v_and_b32_e32 v65, 0x7fffffff, v53
	v_and_b32_e32 v64, 0x7fffffff, v52
	v_pk_fma_f32 v[64:65], v[64:65], s[28:29], 1.0 op_sel_hi:[1,0,0]
	v_pk_mul_f32 v[58:59], v[58:59], v[66:67]
	v_rcp_f32_e32 v64, v64
	v_rcp_f32_e32 v65, v65
	v_pk_mul_f32 v[58:59], v[62:63], v[58:59]
	v_pk_mul_f32 v[62:63], v[52:53], v[52:53]
	v_pk_mul_f32 v[56:57], v[60:61], v[56:57]
	v_pk_fma_f32 v[60:61], v[64:65], s[30:31], v[150:151] op_sel_hi:[1,0,0]
	v_pk_mul_f32 v[62:63], v[62:63], s[74:75] op_sel_hi:[1,0]
	v_pk_fma_f32 v[60:61], v[64:65], v[60:61], s[36:37] op_sel_hi:[1,1,0]
	v_exp_f32_e32 v62, v62
	v_exp_f32_e32 v63, v63
	v_pk_fma_f32 v[60:61], v[64:65], v[60:61], s[50:51] op_sel_hi:[1,1,0]
	v_and_b32_e32 v67, 0x7fffffff, v55
	v_and_b32_e32 v66, 0x7fffffff, v54
	v_pk_fma_f32 v[60:61], v[64:65], v[60:61], s[72:73] op_sel_hi:[1,1,0]
	v_pk_fma_f32 v[66:67], v[66:67], s[28:29], 1.0 op_sel_hi:[1,0,0]
	v_pk_mul_f32 v[60:61], v[64:65], v[60:61]
	v_rcp_f32_e32 v66, v66
	v_rcp_f32_e32 v67, v67
	v_pk_mul_f32 v[60:61], v[62:63], v[60:61]
	v_cmp_gt_f32_e32 vcc, 0, v52
	v_pk_mul_f32 v[62:63], v[52:53], v[60:61]
	v_pk_fma_f32 v[60:61], v[52:53], v[60:61], v[52:53] neg_lo:[1,0,0] neg_hi:[1,0,0]
	v_pk_mul_f32 v[64:65], v[54:55], v[54:55]
	v_cndmask_b32_e32 v52, v60, v62, vcc
	v_cmp_gt_f32_e32 vcc, 0, v53
	s_nop 1
	v_cndmask_b32_e32 v53, v61, v63, vcc
	v_pk_fma_f32 v[60:61], v[66:67], s[30:31], v[150:151] op_sel_hi:[1,0,0]
	v_pk_mul_f32 v[62:63], v[64:65], s[74:75] op_sel_hi:[1,0]
	v_pk_fma_f32 v[60:61], v[66:67], v[60:61], s[36:37] op_sel_hi:[1,1,0]
	v_exp_f32_e32 v62, v62
	v_exp_f32_e32 v63, v63
	v_pk_fma_f32 v[60:61], v[66:67], v[60:61], s[50:51] op_sel_hi:[1,1,0]
	v_mul_f32_e32 v64, 0xbfb8aa3b, v48
	v_pk_fma_f32 v[60:61], v[66:67], v[60:61], s[72:73] op_sel_hi:[1,1,0]
	v_exp_f32_e32 v64, v64
	v_mul_f32_e32 v65, 0xbfb8aa3b, v49
	v_pk_mul_f32 v[60:61], v[66:67], v[60:61]
	v_exp_f32_e32 v65, v65
	v_pk_mul_f32 v[60:61], v[62:63], v[60:61]
	v_cmp_gt_f32_e32 vcc, 0, v54
	v_pk_mul_f32 v[62:63], v[54:55], v[60:61]
	v_pk_fma_f32 v[60:61], v[54:55], v[60:61], v[54:55] neg_lo:[1,0,0] neg_hi:[1,0,0]
	s_nop 0
	v_cndmask_b32_e32 v54, v60, v62, vcc
	v_add_f32_e32 v60, 1.0, v64
	v_mul_f32_e32 v62, 0xbfb8aa3b, v50
	v_rcp_f32_e32 v64, v60
	v_add_f32_e32 v60, 1.0, v65
	v_exp_f32_e32 v62, v62
	v_mul_f32_e32 v65, 0xbfb8aa3b, v51
	v_exp_f32_e32 v67, v65
	v_rcp_f32_e32 v65, v60
	v_add_f32_e32 v60, 1.0, v62
	v_rcp_f32_e32 v66, v60
	v_add_f32_e32 v60, 1.0, v67
	v_rcp_f32_e32 v67, v60
	v_cmp_gt_f32_e32 vcc, 0, v55
	v_pk_mul_f32 v[48:49], v[48:49], v[64:65]
	v_pk_mul_f32 v[50:51], v[50:51], v[66:67]
	v_cndmask_b32_e32 v55, v61, v63, vcc
	v_pk_mul_f32 v[54:55], v[54:55], v[50:51]
	v_pk_mul_f32 v[50:51], v[52:53], v[48:49]
	v_and_b32_e32 v53, 0x7fffffff, v45
	v_and_b32_e32 v52, 0x7fffffff, v44
	v_pk_fma_f32 v[52:53], v[52:53], s[28:29], 1.0 op_sel_hi:[1,0,0]
	v_cvt_pk_bf16_f32 v48, v56, v57
	v_cvt_pk_bf16_f32 v49, v58, v59
	v_cvt_pk_bf16_f32 v50, v50, v51
	v_cvt_pk_bf16_f32 v51, v54, v55
	v_add_co_u32_e32 v54, vcc, s6, v148
; __device__ __forceinline__ unsigned cvt_pk_bf16(float lo, float hi) { unsigned r; asm volatile("v_cvt_pk_bf16_f32 %0, %1, %2" : "=v"(r) : "v"(lo), "v"(hi)); return r; }
; __device__ __forceinline__ float sigmoid_f(float x) { return __builtin_amdgcn_rcpf(1.0f + __builtin_amdgcn_exp2f(-1.44269504f * x)); }
; __device__ __forceinline__ f32x2 gelu_pk(f32x2 v) {
;     const f32x2 av = __builtin_elementwise_abs(v), d = av * 0.2316418882f + 1.0f;
;     f32x2 t; t.x = __builtin_amdgcn_rcpf(d.x); t.y = __builtin_amdgcn_rcpf(d.y);
;     f32x2 q = t * 0.5307027145f + (-0.7265760135f); q = q * t + 0.7107068705f; q = q * t + (-0.142248368f); q = q * t + 0.127414796f; q = q * t;
;     const f32x2 s = (v * v) * (-0.72134752044f);
;     f32x2 e; e.x = __builtin_amdgcn_exp2f(s.x); e.y = __builtin_amdgcn_exp2f(s.y);
;     const f32x2 m = v * (q * e), r = v - m;
;     f32x2 o; o.x = v.x < 0.f ? m.x : r.x; o.y = v.y < 0.f ? m.y : r.y; return o;
; }
; __device__ __forceinline__ f32x4 gelu4(f32x4 v) { f32x2 a = gelu_pk((f32x2){v[0], v[1]}), b = gelu_pk((f32x2){v[2], v[3]}); return (f32x4){a.x, a.y, b.x, b.y}; }
; __device__ __forceinline__ f32x4 sigm4(f32x4 v) { return (f32x4){sigmoid_f(v[0]), sigmoid_f(v[1]), sigmoid_f(v[2]), sigmoid_f(v[3])}; }
; __device__ __forceinline__ f32x4 silu4(f32x4 v) { return v * sigm4(v); }
;     __device__ __forceinline__ void operator()(const f32x4 (&acc)[2][2][4][2], const pg8::Unit& u, int wr, int wc, int fr, int fq) const {
;     ...
;         if (pn < 8) {
;             bf16_t* base = PJ + T_P + 128 * pn + wc * 32 + 8 * fq;
; #pragma unroll
;             for (int ai = 0; ai < 2; ++ai)
; #pragma unroll
;                 for (int m = 0; m < 4; ++m) {
;                     bf16_t* rowp = base + (size_t)(row0 + ai * 128 + m * 16) * 1024;
;                     const f32x4 v0 = gelu4(acc[ai][0][m][0]) * silu4(acc[ai][1][m][0]), v1 = gelu4(acc[ai][0][m][1]) * silu4(acc[ai][1][m][1]);
;                     u32x4 w; w.x = cvt_pk_bf16(v0[0], v0[1]); w.y = cvt_pk_bf16(v0[2], v0[3]); w.z = cvt_pk_bf16(v1[0], v1[1]); w.w = cvt_pk_bf16(v1[2], v1[3]);
;                     __builtin_nontemporal_store(w, (u32x4*)rowp);
;                 }
	v_rcp_f32_e32 v52, v52
	v_rcp_f32_e32 v53, v53
	v_addc_co_u32_e32 v55, vcc, 0, v149, vcc
	global_store_dwordx4 v[54:55], v[48:51], off nt
	v_and_b32_e32 v55, 0x7fffffff, v47
	v_and_b32_e32 v54, 0x7fffffff, v46
	v_pk_mul_f32 v[50:51], v[44:45], v[44:45]
	v_pk_fma_f32 v[48:49], v[52:53], s[30:31], v[150:151] op_sel_hi:[1,0,0]
	v_pk_mul_f32 v[50:51], v[50:51], s[74:75] op_sel_hi:[1,0]
	v_pk_fma_f32 v[48:49], v[52:53], v[48:49], s[36:37] op_sel_hi:[1,1,0]
	v_exp_f32_e32 v50, v50
	v_exp_f32_e32 v51, v51
	v_pk_fma_f32 v[48:49], v[52:53], v[48:49], s[50:51] op_sel_hi:[1,1,0]
	v_pk_fma_f32 v[54:55], v[54:55], s[28:29], 1.0 op_sel_hi:[1,0,0]
	v_pk_fma_f32 v[48:49], v[52:53], v[48:49], s[72:73] op_sel_hi:[1,1,0]
	v_rcp_f32_e32 v54, v54
	v_pk_mul_f32 v[48:49], v[52:53], v[48:49]
	v_rcp_f32_e32 v55, v55
	v_pk_mul_f32 v[48:49], v[50:51], v[48:49]
	v_cmp_gt_f32_e32 vcc, 0, v44
	v_pk_mul_f32 v[50:51], v[44:45], v[48:49]
	v_pk_fma_f32 v[48:49], v[44:45], v[48:49], v[44:45] neg_lo:[1,0,0] neg_hi:[1,0,0]
	v_pk_mul_f32 v[52:53], v[46:47], v[46:47]
	v_cndmask_b32_e32 v44, v48, v50, vcc
	v_cmp_gt_f32_e32 vcc, 0, v45
	s_mov_b32 s6, 0x48000
	s_nop 0
	v_cndmask_b32_e32 v45, v49, v51, vcc
	v_pk_fma_f32 v[48:49], v[54:55], s[30:31], v[150:151] op_sel_hi:[1,0,0]
	v_pk_mul_f32 v[50:51], v[52:53], s[74:75] op_sel_hi:[1,0]
	v_pk_fma_f32 v[48:49], v[54:55], v[48:49], s[36:37] op_sel_hi:[1,1,0]
	v_exp_f32_e32 v50, v50
	v_exp_f32_e32 v51, v51
	v_pk_fma_f32 v[48:49], v[54:55], v[48:49], s[50:51] op_sel_hi:[1,1,0]
	v_cmp_gt_f32_e32 vcc, 0, v46
	v_pk_fma_f32 v[48:49], v[54:55], v[48:49], s[72:73] op_sel_hi:[1,1,0]
	s_nop 0
	v_pk_mul_f32 v[48:49], v[54:55], v[48:49]
	s_nop 0
	v_pk_mul_f32 v[48:49], v[50:51], v[48:49]
	s_nop 0
	v_pk_mul_f32 v[50:51], v[46:47], v[48:49]
	v_pk_fma_f32 v[48:49], v[46:47], v[48:49], v[46:47] neg_lo:[1,0,0] neg_hi:[1,0,0]
	s_nop 0
	v_cndmask_b32_e32 v46, v48, v50, vcc
	v_mul_f32_e32 v50, 0xbfb8aa3b, v41
	v_mul_f32_e32 v48, 0xbfb8aa3b, v40
	v_exp_f32_e32 v50, v50
	v_exp_f32_e32 v48, v48
	v_cmp_gt_f32_e32 vcc, 0, v47
	v_add_f32_e32 v48, 1.0, v48
	s_nop 0
	v_cndmask_b32_e32 v47, v49, v51, vcc
	v_add_f32_e32 v49, 1.0, v50
	v_mul_f32_e32 v50, 0xbfb8aa3b, v42
	v_mul_f32_e32 v51, 0xbfb8aa3b, v43
	v_exp_f32_e32 v50, v50
	v_exp_f32_e32 v51, v51
	v_rcp_f32_e32 v48, v48
	v_rcp_f32_e32 v49, v49
	v_add_f32_e32 v50, 1.0, v50
	v_add_f32_e32 v51, 1.0, v51
	v_rcp_f32_e32 v50, v50
	v_rcp_f32_e32 v51, v51
	v_pk_mul_f32 v[40:41], v[40:41], v[48:49]
	v_and_b32_e32 v49, 0x7fffffff, v37
	v_and_b32_e32 v48, 0x7fffffff, v36
	v_pk_fma_f32 v[48:49], v[48:49], s[28:29], 1.0 op_sel_hi:[1,0,0]
	v_pk_mul_f32 v[42:43], v[42:43], v[50:51]
	v_rcp_f32_e32 v48, v48
	v_rcp_f32_e32 v49, v49
	v_pk_mul_f32 v[42:43], v[46:47], v[42:43]
	v_pk_mul_f32 v[46:47], v[36:37], v[36:37]
	v_pk_mul_f32 v[40:41], v[44:45], v[40:41]
	v_pk_fma_f32 v[44:45], v[48:49], s[30:31], v[150:151] op_sel_hi:[1,0,0]
	v_pk_mul_f32 v[46:47], v[46:47], s[74:75] op_sel_hi:[1,0]
	v_pk_fma_f32 v[44:45], v[48:49], v[44:45], s[36:37] op_sel_hi:[1,1,0]
	v_exp_f32_e32 v46, v46
	v_exp_f32_e32 v47, v47
	v_pk_fma_f32 v[44:45], v[48:49], v[44:45], s[50:51] op_sel_hi:[1,1,0]
	v_and_b32_e32 v51, 0x7fffffff, v39
	v_and_b32_e32 v50, 0x7fffffff, v38
	v_pk_fma_f32 v[44:45], v[48:49], v[44:45], s[72:73] op_sel_hi:[1,1,0]
	v_pk_fma_f32 v[50:51], v[50:51], s[28:29], 1.0 op_sel_hi:[1,0,0]
	v_pk_mul_f32 v[44:45], v[48:49], v[44:45]
	v_rcp_f32_e32 v50, v50
	v_rcp_f32_e32 v51, v51
	v_pk_mul_f32 v[44:45], v[46:47], v[44:45]
	v_cmp_gt_f32_e32 vcc, 0, v36
	v_pk_mul_f32 v[46:47], v[36:37], v[44:45]
	v_pk_fma_f32 v[44:45], v[36:37], v[44:45], v[36:37] neg_lo:[1,0,0] neg_hi:[1,0,0]
	v_pk_mul_f32 v[48:49], v[38:39], v[38:39]
	v_cndmask_b32_e32 v36, v44, v46, vcc
	v_cmp_gt_f32_e32 vcc, 0, v37
	s_nop 1
	v_cndmask_b32_e32 v37, v45, v47, vcc
	v_pk_fma_f32 v[44:45], v[50:51], s[30:31], v[150:151] op_sel_hi:[1,0,0]
	v_pk_mul_f32 v[46:47], v[48:49], s[74:75] op_sel_hi:[1,0]
	v_pk_fma_f32 v[44:45], v[50:51], v[44:45], s[36:37] op_sel_hi:[1,1,0]
	v_exp_f32_e32 v46, v46
	v_exp_f32_e32 v47, v47
	v_pk_fma_f32 v[44:45], v[50:51], v[44:45], s[50:51] op_sel_hi:[1,1,0]
	v_mul_f32_e32 v48, 0xbfb8aa3b, v32
	v_pk_fma_f32 v[44:45], v[50:51], v[44:45], s[72:73] op_sel_hi:[1,1,0]
	v_exp_f32_e32 v48, v48
	v_mul_f32_e32 v49, 0xbfb8aa3b, v33
	v_pk_mul_f32 v[44:45], v[50:51], v[44:45]
	v_exp_f32_e32 v49, v49
	v_pk_mul_f32 v[44:45], v[46:47], v[44:45]
	v_cmp_gt_f32_e32 vcc, 0, v38
	v_pk_mul_f32 v[46:47], v[38:39], v[44:45]
	v_pk_fma_f32 v[44:45], v[38:39], v[44:45], v[38:39] neg_lo:[1,0,0] neg_hi:[1,0,0]
	s_nop 0
	v_cndmask_b32_e32 v38, v44, v46, vcc
	v_add_f32_e32 v44, 1.0, v48
	v_mul_f32_e32 v46, 0xbfb8aa3b, v34
	v_rcp_f32_e32 v48, v44
	v_add_f32_e32 v44, 1.0, v49
	v_exp_f32_e32 v46, v46
	v_mul_f32_e32 v49, 0xbfb8aa3b, v35
	v_exp_f32_e32 v51, v49
	v_rcp_f32_e32 v49, v44
	v_add_f32_e32 v44, 1.0, v46
	v_rcp_f32_e32 v50, v44
	v_add_f32_e32 v44, 1.0, v51
	v_rcp_f32_e32 v51, v44
	v_cmp_gt_f32_e32 vcc, 0, v39
	v_pk_mul_f32 v[32:33], v[32:33], v[48:49]
	v_pk_mul_f32 v[34:35], v[34:35], v[50:51]
	v_cndmask_b32_e32 v39, v45, v47, vcc
	v_pk_mul_f32 v[38:39], v[38:39], v[34:35]
	v_pk_mul_f32 v[34:35], v[36:37], v[32:33]
	v_and_b32_e32 v37, 0x7fffffff, v29
	v_and_b32_e32 v36, 0x7fffffff, v28
	v_pk_fma_f32 v[36:37], v[36:37], s[28:29], 1.0 op_sel_hi:[1,0,0]
	v_cvt_pk_bf16_f32 v32, v40, v41
	v_cvt_pk_bf16_f32 v33, v42, v43
	v_cvt_pk_bf16_f32 v34, v34, v35
	v_cvt_pk_bf16_f32 v35, v38, v39
	v_add_co_u32_e32 v38, vcc, s6, v148
	v_rcp_f32_e32 v36, v36
	v_rcp_f32_e32 v37, v37
	v_addc_co_u32_e32 v39, vcc, 0, v149, vcc
	global_store_dwordx4 v[38:39], v[32:35], off nt
; __device__ __forceinline__ unsigned cvt_pk_bf16(float lo, float hi) { unsigned r; asm volatile("v_cvt_pk_bf16_f32 %0, %1, %2" : "=v"(r) : "v"(lo), "v"(hi)); return r; }
; __device__ __forceinline__ float sigmoid_f(float x) { return __builtin_amdgcn_rcpf(1.0f + __builtin_amdgcn_exp2f(-1.44269504f * x)); }
; __device__ __forceinline__ f32x2 gelu_pk(f32x2 v) {
;     const f32x2 av = __builtin_elementwise_abs(v), d = av * 0.2316418882f + 1.0f;
;     f32x2 t; t.x = __builtin_amdgcn_rcpf(d.x); t.y = __builtin_amdgcn_rcpf(d.y);
;     f32x2 q = t * 0.5307027145f + (-0.7265760135f); q = q * t + 0.7107068705f; q = q * t + (-0.142248368f); q = q * t + 0.127414796f; q = q * t;
;     const f32x2 s = (v * v) * (-0.72134752044f);
;     f32x2 e; e.x = __builtin_amdgcn_exp2f(s.x); e.y = __builtin_amdgcn_exp2f(s.y);
;     const f32x2 m = v * (q * e), r = v - m;
;     f32x2 o; o.x = v.x < 0.f ? m.x : r.x; o.y = v.y < 0.f ? m.y : r.y; return o;
; }
; __device__ __forceinline__ f32x4 gelu4(f32x4 v) { f32x2 a = gelu_pk((f32x2){v[0], v[1]}), b = gelu_pk((f32x2){v[2], v[3]}); return (f32x4){a.x, a.y, b.x, b.y}; }
; __device__ __forceinline__ f32x4 sigm4(f32x4 v) { return (f32x4){sigmoid_f(v[0]), sigmoid_f(v[1]), sigmoid_f(v[2]), sigmoid_f(v[3])}; }
; __device__ __forceinline__ f32x4 silu4(f32x4 v) { return v * sigm4(v); }
;     __device__ __forceinline__ void operator()(const f32x4 (&acc)[2][2][4][2], const pg8::Unit& u, int wr, int wc, int fr, int fq) const {
;     ...
;         if (pn < 8) {
;             bf16_t* base = PJ + T_P + 128 * pn + wc * 32 + 8 * fq;
; #pragma unroll
;             for (int ai = 0; ai < 2; ++ai)
; #pragma unroll
;                 for (int m = 0; m < 4; ++m) {
;                     bf16_t* rowp = base + (size_t)(row0 + ai * 128 + m * 16) * 1024;
;                     const f32x4 v0 = gelu4(acc[ai][0][m][0]) * silu4(acc[ai][1][m][0]), v1 = gelu4(acc[ai][0][m][1]) * silu4(acc[ai][1][m][1]);
;                     u32x4 w; w.x = cvt_pk_bf16(v0[0], v0[1]); w.y = cvt_pk_bf16(v0[2], v0[3]); w.z = cvt_pk_bf16(v1[0], v1[1]); w.w = cvt_pk_bf16(v1[2], v1[3]);
;                     __builtin_nontemporal_store(w, (u32x4*)rowp);
;                 }
	v_and_b32_e32 v39, 0x7fffffff, v31
	v_and_b32_e32 v38, 0x7fffffff, v30
	v_pk_mul_f32 v[34:35], v[28:29], v[28:29]
	v_pk_fma_f32 v[32:33], v[36:37], s[30:31], v[150:151] op_sel_hi:[1,0,0]
	v_pk_mul_f32 v[34:35], v[34:35], s[74:75] op_sel_hi:[1,0]
	v_pk_fma_f32 v[32:33], v[36:37], v[32:33], s[36:37] op_sel_hi:[1,1,0]
	v_exp_f32_e32 v34, v34
	v_exp_f32_e32 v35, v35
	v_pk_fma_f32 v[32:33], v[36:37], v[32:33], s[50:51] op_sel_hi:[1,1,0]
	v_pk_fma_f32 v[38:39], v[38:39], s[28:29], 1.0 op_sel_hi:[1,0,0]
	v_pk_fma_f32 v[32:33], v[36:37], v[32:33], s[72:73] op_sel_hi:[1,1,0]
	v_rcp_f32_e32 v38, v38
	v_pk_mul_f32 v[32:33], v[36:37], v[32:33]
	v_rcp_f32_e32 v39, v39
	v_pk_mul_f32 v[32:33], v[34:35], v[32:33]
	v_cmp_gt_f32_e32 vcc, 0, v28
	v_pk_mul_f32 v[34:35], v[28:29], v[32:33]
	v_pk_fma_f32 v[32:33], v[28:29], v[32:33], v[28:29] neg_lo:[1,0,0] neg_hi:[1,0,0]
	v_pk_mul_f32 v[36:37], v[30:31], v[30:31]
	v_cndmask_b32_e32 v28, v32, v34, vcc
	v_cmp_gt_f32_e32 vcc, 0, v29
	s_mov_b32 s6, 0x50000
	s_nop 0
	v_cndmask_b32_e32 v29, v33, v35, vcc
	v_pk_fma_f32 v[32:33], v[38:39], s[30:31], v[150:151] op_sel_hi:[1,0,0]
	v_pk_mul_f32 v[34:35], v[36:37], s[74:75] op_sel_hi:[1,0]
	v_pk_fma_f32 v[32:33], v[38:39], v[32:33], s[36:37] op_sel_hi:[1,1,0]
	v_exp_f32_e32 v34, v34
	v_exp_f32_e32 v35, v35
	v_pk_fma_f32 v[32:33], v[38:39], v[32:33], s[50:51] op_sel_hi:[1,1,0]
	v_cmp_gt_f32_e32 vcc, 0, v30
	v_pk_fma_f32 v[32:33], v[38:39], v[32:33], s[72:73] op_sel_hi:[1,1,0]
	s_nop 0
	v_pk_mul_f32 v[32:33], v[38:39], v[32:33]
	s_nop 0
	v_pk_mul_f32 v[32:33], v[34:35], v[32:33]
	s_nop 0
	v_pk_mul_f32 v[34:35], v[30:31], v[32:33]
	v_pk_fma_f32 v[32:33], v[30:31], v[32:33], v[30:31] neg_lo:[1,0,0] neg_hi:[1,0,0]
	s_nop 0
	v_cndmask_b32_e32 v30, v32, v34, vcc
	v_mul_f32_e32 v34, 0xbfb8aa3b, v25
	v_mul_f32_e32 v32, 0xbfb8aa3b, v24
	v_exp_f32_e32 v34, v34
	v_exp_f32_e32 v32, v32
	v_cmp_gt_f32_e32 vcc, 0, v31
	v_add_f32_e32 v32, 1.0, v32
	s_nop 0
	v_cndmask_b32_e32 v31, v33, v35, vcc
	v_add_f32_e32 v33, 1.0, v34
	v_mul_f32_e32 v34, 0xbfb8aa3b, v26
	v_mul_f32_e32 v35, 0xbfb8aa3b, v27
	v_exp_f32_e32 v34, v34
	v_exp_f32_e32 v35, v35
	v_rcp_f32_e32 v32, v32
	v_rcp_f32_e32 v33, v33
	v_add_f32_e32 v34, 1.0, v34
	v_add_f32_e32 v35, 1.0, v35
	v_rcp_f32_e32 v34, v34
	v_rcp_f32_e32 v35, v35
	v_pk_mul_f32 v[24:25], v[24:25], v[32:33]
	v_and_b32_e32 v33, 0x7fffffff, v21
	v_and_b32_e32 v32, 0x7fffffff, v20
	v_pk_fma_f32 v[32:33], v[32:33], s[28:29], 1.0 op_sel_hi:[1,0,0]
	v_pk_mul_f32 v[26:27], v[26:27], v[34:35]
	v_rcp_f32_e32 v32, v32
	v_rcp_f32_e32 v33, v33
	v_pk_mul_f32 v[26:27], v[30:31], v[26:27]
	v_pk_mul_f32 v[30:31], v[20:21], v[20:21]
	v_pk_mul_f32 v[24:25], v[28:29], v[24:25]
	v_pk_fma_f32 v[28:29], v[32:33], s[30:31], v[150:151] op_sel_hi:[1,0,0]
	v_pk_mul_f32 v[30:31], v[30:31], s[74:75] op_sel_hi:[1,0]
	v_pk_fma_f32 v[28:29], v[32:33], v[28:29], s[36:37] op_sel_hi:[1,1,0]
	v_exp_f32_e32 v30, v30
	v_exp_f32_e32 v31, v31
	v_pk_fma_f32 v[28:29], v[32:33], v[28:29], s[50:51] op_sel_hi:[1,1,0]
	v_and_b32_e32 v35, 0x7fffffff, v23
	v_and_b32_e32 v34, 0x7fffffff, v22
	v_pk_fma_f32 v[28:29], v[32:33], v[28:29], s[72:73] op_sel_hi:[1,1,0]
	v_pk_fma_f32 v[34:35], v[34:35], s[28:29], 1.0 op_sel_hi:[1,0,0]
	v_pk_mul_f32 v[28:29], v[32:33], v[28:29]
	v_rcp_f32_e32 v34, v34
	v_rcp_f32_e32 v35, v35
	v_pk_mul_f32 v[28:29], v[30:31], v[28:29]
	v_cmp_gt_f32_e32 vcc, 0, v20
	v_pk_mul_f32 v[30:31], v[20:21], v[28:29]
	v_pk_fma_f32 v[28:29], v[20:21], v[28:29], v[20:21] neg_lo:[1,0,0] neg_hi:[1,0,0]
	v_pk_mul_f32 v[32:33], v[22:23], v[22:23]
	v_cndmask_b32_e32 v20, v28, v30, vcc
	v_cmp_gt_f32_e32 vcc, 0, v21
	s_nop 1
	v_cndmask_b32_e32 v21, v29, v31, vcc
	v_pk_fma_f32 v[28:29], v[34:35], s[30:31], v[150:151] op_sel_hi:[1,0,0]
	v_pk_mul_f32 v[30:31], v[32:33], s[74:75] op_sel_hi:[1,0]
	v_pk_fma_f32 v[28:29], v[34:35], v[28:29], s[36:37] op_sel_hi:[1,1,0]
	v_exp_f32_e32 v30, v30
	v_exp_f32_e32 v31, v31
	v_pk_fma_f32 v[28:29], v[34:35], v[28:29], s[50:51] op_sel_hi:[1,1,0]
	v_mul_f32_e32 v32, 0xbfb8aa3b, v16
	v_pk_fma_f32 v[28:29], v[34:35], v[28:29], s[72:73] op_sel_hi:[1,1,0]
	v_exp_f32_e32 v32, v32
	v_mul_f32_e32 v33, 0xbfb8aa3b, v17
	v_pk_mul_f32 v[28:29], v[34:35], v[28:29]
	v_exp_f32_e32 v33, v33
	v_pk_mul_f32 v[28:29], v[30:31], v[28:29]
	v_cmp_gt_f32_e32 vcc, 0, v22
	v_pk_mul_f32 v[30:31], v[22:23], v[28:29]
	v_pk_fma_f32 v[28:29], v[22:23], v[28:29], v[22:23] neg_lo:[1,0,0] neg_hi:[1,0,0]
	s_nop 0
	v_cndmask_b32_e32 v22, v28, v30, vcc
	v_add_f32_e32 v28, 1.0, v32
	v_mul_f32_e32 v30, 0xbfb8aa3b, v18
	v_rcp_f32_e32 v32, v28
	v_add_f32_e32 v28, 1.0, v33
	v_exp_f32_e32 v30, v30
	v_mul_f32_e32 v33, 0xbfb8aa3b, v19
	v_exp_f32_e32 v35, v33
	v_rcp_f32_e32 v33, v28
	v_add_f32_e32 v28, 1.0, v30
	v_rcp_f32_e32 v34, v28
	v_add_f32_e32 v28, 1.0, v35
	v_rcp_f32_e32 v35, v28
	v_cmp_gt_f32_e32 vcc, 0, v23
	v_pk_mul_f32 v[16:17], v[16:17], v[32:33]
	v_pk_mul_f32 v[18:19], v[18:19], v[34:35]
	v_cndmask_b32_e32 v23, v29, v31, vcc
	v_pk_mul_f32 v[22:23], v[22:23], v[18:19]
	v_pk_mul_f32 v[18:19], v[20:21], v[16:17]
	v_and_b32_e32 v21, 0x7fffffff, v13
	v_and_b32_e32 v20, 0x7fffffff, v12
	v_pk_fma_f32 v[20:21], v[20:21], s[28:29], 1.0 op_sel_hi:[1,0,0]
	v_cvt_pk_bf16_f32 v16, v24, v25
	v_cvt_pk_bf16_f32 v17, v26, v27
	v_cvt_pk_bf16_f32 v18, v18, v19
	v_cvt_pk_bf16_f32 v19, v22, v23
	v_add_co_u32_e32 v22, vcc, s6, v148
	v_rcp_f32_e32 v20, v20
	v_rcp_f32_e32 v21, v21
; __device__ __forceinline__ unsigned cvt_pk_bf16(float lo, float hi) { unsigned r; asm volatile("v_cvt_pk_bf16_f32 %0, %1, %2" : "=v"(r) : "v"(lo), "v"(hi)); return r; }
; __device__ __forceinline__ float sigmoid_f(float x) { return __builtin_amdgcn_rcpf(1.0f + __builtin_amdgcn_exp2f(-1.44269504f * x)); }
; __device__ __forceinline__ f32x2 gelu_pk(f32x2 v) {
;     const f32x2 av = __builtin_elementwise_abs(v), d = av * 0.2316418882f + 1.0f;
;     f32x2 t; t.x = __builtin_amdgcn_rcpf(d.x); t.y = __builtin_amdgcn_rcpf(d.y);
;     f32x2 q = t * 0.5307027145f + (-0.7265760135f); q = q * t + 0.7107068705f; q = q * t + (-0.142248368f); q = q * t + 0.127414796f; q = q * t;
;     const f32x2 s = (v * v) * (-0.72134752044f);
;     f32x2 e; e.x = __builtin_amdgcn_exp2f(s.x); e.y = __builtin_amdgcn_exp2f(s.y);
;     const f32x2 m = v * (q * e), r = v - m;
;     f32x2 o; o.x = v.x < 0.f ? m.x : r.x; o.y = v.y < 0.f ? m.y : r.y; return o;
; }
; __device__ __forceinline__ f32x4 gelu4(f32x4 v) { f32x2 a = gelu_pk((f32x2){v[0], v[1]}), b = gelu_pk((f32x2){v[2], v[3]}); return (f32x4){a.x, a.y, b.x, b.y}; }
; __device__ __forceinline__ f32x4 sigm4(f32x4 v) { return (f32x4){sigmoid_f(v[0]), sigmoid_f(v[1]), sigmoid_f(v[2]), sigmoid_f(v[3])}; }
; __device__ __forceinline__ f32x4 silu4(f32x4 v) { return v * sigm4(v); }
;     __device__ __forceinline__ void operator()(const f32x4 (&acc)[2][2][4][2], const pg8::Unit& u, int wr, int wc, int fr, int fq) const {
;     ...
;         if (pn < 8) {
;             bf16_t* base = PJ + T_P + 128 * pn + wc * 32 + 8 * fq;
; #pragma unroll
;             for (int ai = 0; ai < 2; ++ai)
; #pragma unroll
;                 for (int m = 0; m < 4; ++m) {
;                     bf16_t* rowp = base + (size_t)(row0 + ai * 128 + m * 16) * 1024;
;                     const f32x4 v0 = gelu4(acc[ai][0][m][0]) * silu4(acc[ai][1][m][0]), v1 = gelu4(acc[ai][0][m][1]) * silu4(acc[ai][1][m][1]);
;                     u32x4 w; w.x = cvt_pk_bf16(v0[0], v0[1]); w.y = cvt_pk_bf16(v0[2], v0[3]); w.z = cvt_pk_bf16(v1[0], v1[1]); w.w = cvt_pk_bf16(v1[2], v1[3]);
;                     __builtin_nontemporal_store(w, (u32x4*)rowp);
;                 }
	v_addc_co_u32_e32 v23, vcc, 0, v149, vcc
	global_store_dwordx4 v[22:23], v[16:19], off nt
	v_and_b32_e32 v23, 0x7fffffff, v15
	v_and_b32_e32 v22, 0x7fffffff, v14
	v_pk_mul_f32 v[18:19], v[12:13], v[12:13]
	v_pk_fma_f32 v[16:17], v[20:21], s[30:31], v[150:151] op_sel_hi:[1,0,0]
	v_pk_mul_f32 v[18:19], v[18:19], s[74:75] op_sel_hi:[1,0]
	v_pk_fma_f32 v[16:17], v[20:21], v[16:17], s[36:37] op_sel_hi:[1,1,0]
	v_exp_f32_e32 v18, v18
	v_exp_f32_e32 v19, v19
	v_pk_fma_f32 v[16:17], v[20:21], v[16:17], s[50:51] op_sel_hi:[1,1,0]
	v_pk_fma_f32 v[22:23], v[22:23], s[28:29], 1.0 op_sel_hi:[1,0,0]
	v_pk_fma_f32 v[16:17], v[20:21], v[16:17], s[72:73] op_sel_hi:[1,1,0]
	v_rcp_f32_e32 v22, v22
	v_pk_mul_f32 v[16:17], v[20:21], v[16:17]
	v_rcp_f32_e32 v23, v23
	v_pk_mul_f32 v[16:17], v[18:19], v[16:17]
	v_cmp_gt_f32_e32 vcc, 0, v12
	v_pk_mul_f32 v[18:19], v[12:13], v[16:17]
	v_pk_fma_f32 v[16:17], v[12:13], v[16:17], v[12:13] neg_lo:[1,0,0] neg_hi:[1,0,0]
	v_pk_mul_f32 v[20:21], v[14:15], v[14:15]
	v_cndmask_b32_e32 v12, v16, v18, vcc
	v_cmp_gt_f32_e32 vcc, 0, v13
	s_nop 1
	v_cndmask_b32_e32 v13, v17, v19, vcc
	v_pk_fma_f32 v[16:17], v[22:23], s[30:31], v[150:151] op_sel_hi:[1,0,0]
	v_pk_mul_f32 v[18:19], v[20:21], s[74:75] op_sel_hi:[1,0]
	v_pk_fma_f32 v[16:17], v[22:23], v[16:17], s[36:37] op_sel_hi:[1,1,0]
	v_exp_f32_e32 v18, v18
	v_exp_f32_e32 v19, v19
	v_pk_fma_f32 v[16:17], v[22:23], v[16:17], s[50:51] op_sel_hi:[1,1,0]
	v_cmp_gt_f32_e32 vcc, 0, v14
	v_pk_fma_f32 v[16:17], v[22:23], v[16:17], s[72:73] op_sel_hi:[1,1,0]
	s_nop 0
	v_pk_mul_f32 v[16:17], v[22:23], v[16:17]
	s_nop 0
	v_pk_mul_f32 v[16:17], v[18:19], v[16:17]
	s_nop 0
	v_pk_mul_f32 v[18:19], v[14:15], v[16:17]
	v_pk_fma_f32 v[16:17], v[14:15], v[16:17], v[14:15] neg_lo:[1,0,0] neg_hi:[1,0,0]
	s_nop 0
	v_cndmask_b32_e32 v14, v16, v18, vcc
	v_mul_f32_e32 v18, 0xbfb8aa3b, v9
	v_mul_f32_e32 v16, 0xbfb8aa3b, v8
	v_exp_f32_e32 v18, v18
	v_exp_f32_e32 v16, v16
	v_cmp_gt_f32_e32 vcc, 0, v15
	v_add_f32_e32 v16, 1.0, v16
	s_nop 0
	v_cndmask_b32_e32 v15, v17, v19, vcc
	v_add_f32_e32 v17, 1.0, v18
	v_mul_f32_e32 v18, 0xbfb8aa3b, v10
	v_mul_f32_e32 v19, 0xbfb8aa3b, v11
	v_exp_f32_e32 v18, v18
	v_exp_f32_e32 v19, v19
	v_rcp_f32_e32 v16, v16
	v_rcp_f32_e32 v17, v17
	v_add_f32_e32 v18, 1.0, v18
	v_add_f32_e32 v19, 1.0, v19
	v_rcp_f32_e32 v18, v18
	v_rcp_f32_e32 v19, v19
	v_pk_mul_f32 v[8:9], v[8:9], v[16:17]
	v_and_b32_e32 v17, 0x7fffffff, v5
	v_and_b32_e32 v16, 0x7fffffff, v4
	v_pk_fma_f32 v[16:17], v[16:17], s[28:29], 1.0 op_sel_hi:[1,0,0]
	v_pk_mul_f32 v[10:11], v[10:11], v[18:19]
	v_rcp_f32_e32 v16, v16
	v_rcp_f32_e32 v17, v17
	v_pk_mul_f32 v[10:11], v[14:15], v[10:11]
	v_pk_mul_f32 v[14:15], v[4:5], v[4:5]
	v_pk_mul_f32 v[8:9], v[12:13], v[8:9]
	v_pk_fma_f32 v[12:13], v[16:17], s[30:31], v[150:151] op_sel_hi:[1,0,0]
	v_pk_mul_f32 v[14:15], v[14:15], s[74:75] op_sel_hi:[1,0]
	v_pk_fma_f32 v[12:13], v[16:17], v[12:13], s[36:37] op_sel_hi:[1,1,0]
	v_exp_f32_e32 v14, v14
	v_exp_f32_e32 v15, v15
	v_pk_fma_f32 v[12:13], v[16:17], v[12:13], s[50:51] op_sel_hi:[1,1,0]
	v_and_b32_e32 v19, 0x7fffffff, v7
	v_and_b32_e32 v18, 0x7fffffff, v6
	v_pk_fma_f32 v[12:13], v[16:17], v[12:13], s[72:73] op_sel_hi:[1,1,0]
	v_pk_fma_f32 v[18:19], v[18:19], s[28:29], 1.0 op_sel_hi:[1,0,0]
	v_pk_mul_f32 v[12:13], v[16:17], v[12:13]
	v_rcp_f32_e32 v18, v18
	v_rcp_f32_e32 v19, v19
	v_pk_mul_f32 v[12:13], v[14:15], v[12:13]
	v_cmp_gt_f32_e32 vcc, 0, v4
	v_pk_mul_f32 v[14:15], v[4:5], v[12:13]
	v_pk_fma_f32 v[12:13], v[4:5], v[12:13], v[4:5] neg_lo:[1,0,0] neg_hi:[1,0,0]
	v_pk_mul_f32 v[16:17], v[6:7], v[6:7]
	v_cndmask_b32_e32 v4, v12, v14, vcc
	v_cmp_gt_f32_e32 vcc, 0, v5
	s_nop 1
	v_cndmask_b32_e32 v5, v13, v15, vcc
	v_pk_fma_f32 v[12:13], v[18:19], s[30:31], v[150:151] op_sel_hi:[1,0,0]
	v_pk_mul_f32 v[14:15], v[16:17], s[74:75] op_sel_hi:[1,0]
	v_pk_fma_f32 v[12:13], v[18:19], v[12:13], s[36:37] op_sel_hi:[1,1,0]
	v_exp_f32_e32 v14, v14
	v_exp_f32_e32 v15, v15
	v_pk_fma_f32 v[12:13], v[18:19], v[12:13], s[50:51] op_sel_hi:[1,1,0]
	v_mul_f32_e32 v16, 0xbfb8aa3b, v0
	v_pk_fma_f32 v[12:13], v[18:19], v[12:13], s[72:73] op_sel_hi:[1,1,0]
	v_exp_f32_e32 v16, v16
	v_mul_f32_e32 v17, 0xbfb8aa3b, v1
	v_pk_mul_f32 v[12:13], v[18:19], v[12:13]
	v_exp_f32_e32 v17, v17
	v_pk_mul_f32 v[12:13], v[14:15], v[12:13]
	v_cmp_gt_f32_e32 vcc, 0, v6
	v_pk_mul_f32 v[14:15], v[6:7], v[12:13]
	v_pk_fma_f32 v[12:13], v[6:7], v[12:13], v[6:7] neg_lo:[1,0,0] neg_hi:[1,0,0]
	s_nop 0
	v_cndmask_b32_e32 v6, v12, v14, vcc
	v_add_f32_e32 v12, 1.0, v16
	v_mul_f32_e32 v14, 0xbfb8aa3b, v2
	v_rcp_f32_e32 v16, v12
	v_add_f32_e32 v12, 1.0, v17
	v_exp_f32_e32 v14, v14
	v_mul_f32_e32 v17, 0xbfb8aa3b, v3
	v_exp_f32_e32 v19, v17
	v_rcp_f32_e32 v17, v12
	v_add_f32_e32 v12, 1.0, v14
	v_rcp_f32_e32 v18, v12
	v_add_f32_e32 v12, 1.0, v19
	v_rcp_f32_e32 v19, v12
	v_cmp_gt_f32_e32 vcc, 0, v7
	v_pk_mul_f32 v[0:1], v[0:1], v[16:17]
	v_pk_mul_f32 v[2:3], v[2:3], v[18:19]
	v_cndmask_b32_e32 v7, v13, v15, vcc
	v_pk_mul_f32 v[6:7], v[6:7], v[2:3]
	v_pk_mul_f32 v[2:3], v[4:5], v[0:1]
	v_add_co_u32_e32 v4, vcc, 0x58000, v148
	v_cvt_pk_bf16_f32 v0, v8, v9
	v_cvt_pk_bf16_f32 v1, v10, v11
	v_cvt_pk_bf16_f32 v2, v2, v3
	v_cvt_pk_bf16_f32 v3, v6, v7
	s_nop 1
	v_addc_co_u32_e32 v5, vcc, 0, v149, vcc
	global_store_dwordx4 v[4:5], v[0:3], off nt
	s_andn2_b64 vcc, exec, s[4:5]
	s_mov_b64 s[4:5], -1
	s_cbranch_vccnz .LBB0_152
